# v49 + GEMM K-loops: s_setprio 1 moved above the MMA-opening barrier, redundant post-barrier lgkmcnt(0) dropped, vmcnt/lgkmcnt waits merged, m0 wait states filled with the address add
# baseline (speedup 1.0000x reference)
.LBB0_220:
	ds_read_b128 v[148:151], v173
	ds_read_b128 v[152:155], v173 offset:1024
	ds_read_b128 v[156:159], v173 offset:2048
	ds_read_b128 v[160:163], v173 offset:3072
	ds_read_b128 v[164:167], v174
	ds_read_b128 v[180:183], v174 offset:1024
	ds_read_b128 v[184:187], v174 offset:2048
	ds_read_b128 v[188:191], v174 offset:3072
	s_add_u32 s52, s50, 0xfffc0080
	s_addc_u32 s53, s51, -1
	s_cmp_eq_u32 s66, 12
	s_cselect_b32 s55, s9, s53
	s_cselect_b32 s54, s11, s52
	s_cselect_b32 s53, s20, s45
	s_cselect_b32 s52, s33, s43
	v_lshl_add_u64 v[168:169], s[50:51], 0, v[140:141]
	s_add_i32 m0, s35, 0xc000
	ds_read_b128 v[192:195], v175
	ds_read_b128 v[196:199], v175 offset:1024
	ds_read_b128 v[204:207], v175 offset:2048
	ds_read_b128 v[208:211], v175 offset:3072
	ds_read_b128 v[212:215], v175 offset:4096
	ds_read_b128 v[216:219], v175 offset:5120
	ds_read_b128 v[220:223], v175 offset:6144
	ds_read_b128 v[224:227], v175 offset:7168
	global_load_lds_dwordx4 v[168:169], off
	s_add_i32 m0, s35, 0xe000
	v_lshl_add_u64 v[168:169], s[50:51], 0, v[142:143]
	global_load_lds_dwordx4 v[168:169], off
	s_waitcnt vmcnt(8) lgkmcnt(0)
	s_setprio 1
	s_barrier
	v_mfma_f32_16x16x32_bf16 v[124:127], v[148:151], v[192:195], v[124:127]
	v_mfma_f32_16x16x32_bf16 v[120:123], v[156:159], v[192:195], v[120:123]
	v_mfma_f32_16x16x32_bf16 v[108:111], v[148:151], v[204:207], v[108:111]
	v_mfma_f32_16x16x32_bf16 v[104:107], v[156:159], v[204:207], v[104:107]
	v_mfma_f32_16x16x32_bf16 v[92:95], v[148:151], v[212:215], v[92:95]
	v_mfma_f32_16x16x32_bf16 v[88:91], v[156:159], v[212:215], v[88:91]
	v_mfma_f32_16x16x32_bf16 v[76:79], v[148:151], v[220:223], v[76:79]
	v_mfma_f32_16x16x32_bf16 v[72:75], v[156:159], v[220:223], v[72:75]
	v_mfma_f32_16x16x32_bf16 v[124:127], v[152:155], v[196:199], v[124:127]
	v_mfma_f32_16x16x32_bf16 v[120:123], v[160:163], v[196:199], v[120:123]
	v_mfma_f32_16x16x32_bf16 v[108:111], v[152:155], v[208:211], v[108:111]
	v_mfma_f32_16x16x32_bf16 v[104:107], v[160:163], v[208:211], v[104:107]
	v_mfma_f32_16x16x32_bf16 v[92:95], v[152:155], v[216:219], v[92:95]
	v_mfma_f32_16x16x32_bf16 v[88:91], v[160:163], v[216:219], v[88:91]
	v_mfma_f32_16x16x32_bf16 v[76:79], v[152:155], v[224:227], v[76:79]
	v_mfma_f32_16x16x32_bf16 v[72:75], v[160:163], v[224:227], v[72:75]
	s_setprio 0
	s_setprio 1
	v_mfma_f32_16x16x32_bf16 v[116:119], v[164:167], v[192:195], v[116:119]
	v_mfma_f32_16x16x32_bf16 v[112:115], v[184:187], v[192:195], v[112:115]
	v_mfma_f32_16x16x32_bf16 v[100:103], v[164:167], v[204:207], v[100:103]
	v_mfma_f32_16x16x32_bf16 v[96:99], v[184:187], v[204:207], v[96:99]
	v_mfma_f32_16x16x32_bf16 v[84:87], v[164:167], v[212:215], v[84:87]
	v_mfma_f32_16x16x32_bf16 v[80:83], v[184:187], v[212:215], v[80:83]
	v_mfma_f32_16x16x32_bf16 v[68:71], v[164:167], v[220:223], v[68:71]
	v_mfma_f32_16x16x32_bf16 v[64:67], v[184:187], v[220:223], v[64:67]
	v_mfma_f32_16x16x32_bf16 v[116:119], v[180:183], v[196:199], v[116:119]
	v_mfma_f32_16x16x32_bf16 v[112:115], v[188:191], v[196:199], v[112:115]
	v_mfma_f32_16x16x32_bf16 v[100:103], v[180:183], v[208:211], v[100:103]
	v_mfma_f32_16x16x32_bf16 v[96:99], v[188:191], v[208:211], v[96:99]
	v_mfma_f32_16x16x32_bf16 v[84:87], v[180:183], v[216:219], v[84:87]
	v_mfma_f32_16x16x32_bf16 v[80:83], v[188:191], v[216:219], v[80:83]
	v_mfma_f32_16x16x32_bf16 v[68:71], v[180:183], v[224:227], v[68:71]
	v_mfma_f32_16x16x32_bf16 v[64:67], v[188:191], v[224:227], v[64:67]
	s_setprio 0
	s_barrier
	s_add_i32 s67, s63, s31
	v_lshl_add_u64 v[168:169], s[52:53], 0, v[130:131]
	s_mov_b32 m0, s67
	ds_read_b128 v[192:195], v175 offset:16384
	ds_read_b128 v[196:199], v175 offset:17408
	ds_read_b128 v[204:207], v175 offset:18432
	ds_read_b128 v[208:211], v175 offset:19456
	ds_read_b128 v[212:215], v175 offset:20480
	ds_read_b128 v[216:219], v175 offset:21504
	ds_read_b128 v[220:223], v175 offset:22528
	ds_read_b128 v[224:227], v175 offset:23552
	global_load_lds_dwordx4 v[168:169], off
	s_add_i32 m0, s67, 0x2000
	s_add_u32 s68, s52, 0x40000
	v_lshl_add_u64 v[200:201], s[52:53], 0, v[134:135]
	s_addc_u32 s69, s53, 0
	s_add_i32 s67, s64, s31
	global_load_lds_dwordx4 v[200:201], off
	v_lshl_add_u64 v[228:229], s[68:69], 0, v[130:131]
	s_mov_b32 m0, s67
	v_lshl_add_u64 v[230:231], s[54:55], 0, v[132:133]
	global_load_lds_dwordx4 v[228:229], off
	s_add_i32 m0, s67, 0x2000
	v_lshl_add_u64 v[228:229], s[68:69], 0, v[134:135]
	global_load_lds_dwordx4 v[228:229], off
	s_mov_b32 m0, s35
	v_lshl_add_u64 v[228:229], s[54:55], 0, v[128:129]
	global_load_lds_dwordx4 v[228:229], off
	s_mov_b32 m0, s37
	s_nop 0
	global_load_lds_dwordx4 v[230:231], off
	s_waitcnt vmcnt(8) lgkmcnt(0)
	s_setprio 1
	s_barrier
	v_mfma_f32_16x16x32_bf16 v[60:63], v[148:151], v[192:195], v[60:63]
	v_mfma_f32_16x16x32_bf16 v[56:59], v[156:159], v[192:195], v[56:59]
	v_mfma_f32_16x16x32_bf16 v[44:47], v[148:151], v[204:207], v[44:47]
	v_mfma_f32_16x16x32_bf16 v[40:43], v[156:159], v[204:207], v[40:43]
	v_mfma_f32_16x16x32_bf16 v[28:31], v[148:151], v[212:215], v[28:31]
	v_mfma_f32_16x16x32_bf16 v[24:27], v[156:159], v[212:215], v[24:27]
	v_mfma_f32_16x16x32_bf16 v[12:15], v[148:151], v[220:223], v[12:15]
	v_mfma_f32_16x16x32_bf16 v[8:11], v[156:159], v[220:223], v[8:11]
	v_mfma_f32_16x16x32_bf16 v[60:63], v[152:155], v[196:199], v[60:63]
	v_mfma_f32_16x16x32_bf16 v[56:59], v[160:163], v[196:199], v[56:59]
	v_mfma_f32_16x16x32_bf16 v[44:47], v[152:155], v[208:211], v[44:47]
	v_mfma_f32_16x16x32_bf16 v[40:43], v[160:163], v[208:211], v[40:43]
	v_mfma_f32_16x16x32_bf16 v[28:31], v[152:155], v[216:219], v[28:31]
	v_mfma_f32_16x16x32_bf16 v[24:27], v[160:163], v[216:219], v[24:27]
	v_mfma_f32_16x16x32_bf16 v[12:15], v[152:155], v[224:227], v[12:15]
	v_mfma_f32_16x16x32_bf16 v[8:11], v[160:163], v[224:227], v[8:11]
	s_setprio 0
	s_setprio 1
	v_mfma_f32_16x16x32_bf16 v[52:55], v[164:167], v[192:195], v[52:55]
	v_mfma_f32_16x16x32_bf16 v[48:51], v[184:187], v[192:195], v[48:51]
	v_mfma_f32_16x16x32_bf16 v[36:39], v[164:167], v[204:207], v[36:39]
	v_mfma_f32_16x16x32_bf16 v[32:35], v[184:187], v[204:207], v[32:35]
	v_mfma_f32_16x16x32_bf16 v[20:23], v[164:167], v[212:215], v[20:23]
	v_mfma_f32_16x16x32_bf16 v[16:19], v[184:187], v[212:215], v[16:19]
	v_mfma_f32_16x16x32_bf16 v[4:7], v[164:167], v[220:223], v[4:7]
	v_mfma_f32_16x16x32_bf16 v[0:3], v[184:187], v[220:223], v[0:3]
	v_mfma_f32_16x16x32_bf16 v[52:55], v[180:183], v[196:199], v[52:55]
	v_mfma_f32_16x16x32_bf16 v[48:51], v[188:191], v[196:199], v[48:51]
	v_mfma_f32_16x16x32_bf16 v[36:39], v[180:183], v[208:211], v[36:39]
	v_mfma_f32_16x16x32_bf16 v[32:35], v[188:191], v[208:211], v[32:35]
	v_mfma_f32_16x16x32_bf16 v[20:23], v[180:183], v[216:219], v[20:23]
	v_mfma_f32_16x16x32_bf16 v[16:19], v[188:191], v[216:219], v[16:19]
	v_mfma_f32_16x16x32_bf16 v[4:7], v[180:183], v[224:227], v[4:7]
	v_mfma_f32_16x16x32_bf16 v[0:3], v[188:191], v[224:227], v[0:3]
	s_setprio 0
	s_barrier
	s_add_i32 s67, 0, 0x18000
	v_add_u32_e32 v137, s67, v171
	s_add_i32 s68, 0, 0x1c000
	ds_read_b128 v[148:151], v137
	ds_read_b128 v[152:155], v137 offset:1024
	ds_read_b128 v[156:159], v137 offset:2048
	ds_read_b128 v[160:163], v137 offset:3072
	v_add_u32_e32 v137, s68, v171
	ds_read_b128 v[164:167], v137
	ds_read_b128 v[180:183], v137 offset:1024
	ds_read_b128 v[184:187], v137 offset:2048
	ds_read_b128 v[188:191], v137 offset:3072
	s_add_u32 s54, s54, 0x40000
	s_addc_u32 s55, s55, 0
	s_mov_b32 m0, s39
	v_lshl_add_u64 v[232:233], s[54:55], 0, v[128:129]
	ds_read_b128 v[192:195], v175 offset:32768
	ds_read_b128 v[196:199], v175 offset:33792
	ds_read_b128 v[204:207], v175 offset:34816
	ds_read_b128 v[208:211], v175 offset:35840
	ds_read_b128 v[212:215], v175 offset:36864
	ds_read_b128 v[216:219], v175 offset:37888
	ds_read_b128 v[220:223], v175 offset:38912
	ds_read_b128 v[224:227], v175 offset:39936
	global_load_lds_dwordx4 v[232:233], off
	s_mov_b32 m0, s41
	v_lshl_add_u64 v[232:233], s[54:55], 0, v[132:133]
	global_load_lds_dwordx4 v[232:233], off
	s_waitcnt vmcnt(8) lgkmcnt(0)
	s_setprio 1
	s_barrier
	v_mfma_f32_16x16x32_bf16 v[124:127], v[148:151], v[192:195], v[124:127]
	v_mfma_f32_16x16x32_bf16 v[120:123], v[156:159], v[192:195], v[120:123]
	v_mfma_f32_16x16x32_bf16 v[108:111], v[148:151], v[204:207], v[108:111]
	v_mfma_f32_16x16x32_bf16 v[104:107], v[156:159], v[204:207], v[104:107]
	v_mfma_f32_16x16x32_bf16 v[92:95], v[148:151], v[212:215], v[92:95]
	v_mfma_f32_16x16x32_bf16 v[88:91], v[156:159], v[212:215], v[88:91]
	v_mfma_f32_16x16x32_bf16 v[76:79], v[148:151], v[220:223], v[76:79]
	v_mfma_f32_16x16x32_bf16 v[72:75], v[156:159], v[220:223], v[72:75]
	v_mfma_f32_16x16x32_bf16 v[124:127], v[152:155], v[196:199], v[124:127]
	v_mfma_f32_16x16x32_bf16 v[120:123], v[160:163], v[196:199], v[120:123]
	v_mfma_f32_16x16x32_bf16 v[108:111], v[152:155], v[208:211], v[108:111]
	v_mfma_f32_16x16x32_bf16 v[104:107], v[160:163], v[208:211], v[104:107]
	v_mfma_f32_16x16x32_bf16 v[92:95], v[152:155], v[216:219], v[92:95]
	v_mfma_f32_16x16x32_bf16 v[88:91], v[160:163], v[216:219], v[88:91]
	v_mfma_f32_16x16x32_bf16 v[76:79], v[152:155], v[224:227], v[76:79]
	v_mfma_f32_16x16x32_bf16 v[72:75], v[160:163], v[224:227], v[72:75]
	s_setprio 0
	s_setprio 1
	v_mfma_f32_16x16x32_bf16 v[116:119], v[164:167], v[192:195], v[116:119]
	v_mfma_f32_16x16x32_bf16 v[112:115], v[184:187], v[192:195], v[112:115]
	v_mfma_f32_16x16x32_bf16 v[100:103], v[164:167], v[204:207], v[100:103]
	v_mfma_f32_16x16x32_bf16 v[96:99], v[184:187], v[204:207], v[96:99]
	v_mfma_f32_16x16x32_bf16 v[84:87], v[164:167], v[212:215], v[84:87]
	v_mfma_f32_16x16x32_bf16 v[80:83], v[184:187], v[212:215], v[80:83]
	v_mfma_f32_16x16x32_bf16 v[68:71], v[164:167], v[220:223], v[68:71]
	v_mfma_f32_16x16x32_bf16 v[64:67], v[184:187], v[220:223], v[64:67]
	v_mfma_f32_16x16x32_bf16 v[116:119], v[180:183], v[196:199], v[116:119]
	v_mfma_f32_16x16x32_bf16 v[112:115], v[188:191], v[196:199], v[112:115]
	v_mfma_f32_16x16x32_bf16 v[100:103], v[180:183], v[208:211], v[100:103]
	v_mfma_f32_16x16x32_bf16 v[96:99], v[188:191], v[208:211], v[96:99]
	v_mfma_f32_16x16x32_bf16 v[84:87], v[180:183], v[216:219], v[84:87]
	v_mfma_f32_16x16x32_bf16 v[80:83], v[188:191], v[216:219], v[80:83]
	v_mfma_f32_16x16x32_bf16 v[68:71], v[180:183], v[224:227], v[68:71]
	v_mfma_f32_16x16x32_bf16 v[64:67], v[188:191], v[224:227], v[64:67]
	s_setprio 0
	s_barrier
	s_add_i32 s54, s67, s31
	v_lshl_add_u64 v[168:169], v[168:169], 0, s[22:23]
	s_mov_b32 m0, s54
	ds_read_b128 v[192:195], v175 offset:49152
	ds_read_b128 v[196:199], v175 offset:50176
	ds_read_b128 v[204:207], v175 offset:51200
	ds_read_b128 v[208:211], v175 offset:52224
	ds_read_b128 v[212:215], v175 offset:53248
	ds_read_b128 v[216:219], v175 offset:54272
	ds_read_b128 v[220:223], v175 offset:55296
	ds_read_b128 v[224:227], v175 offset:56320
	global_load_lds_dwordx4 v[168:169], off
	s_add_i32 m0, s54, 0x2000
	s_add_u32 s52, s52, 0x40080
	v_lshl_add_u64 v[168:169], v[200:201], 0, s[22:23]
	s_addc_u32 s53, s53, 0
	s_add_i32 s54, s68, s31
	global_load_lds_dwordx4 v[168:169], off
	s_mov_b32 m0, s54
	v_lshl_add_u64 v[168:169], s[52:53], 0, v[130:131]
	global_load_lds_dwordx4 v[168:169], off
	s_add_i32 m0, s54, 0x2000
	v_lshl_add_u64 v[168:169], s[52:53], 0, v[134:135]
	global_load_lds_dwordx4 v[168:169], off
	s_mov_b32 m0, s60
	v_lshl_add_u64 v[168:169], v[228:229], 0, s[22:23]
	global_load_lds_dwordx4 v[168:169], off
	s_mov_b32 m0, s61
	v_lshl_add_u64 v[168:169], v[230:231], 0, s[22:23]
	global_load_lds_dwordx4 v[168:169], off
	s_waitcnt vmcnt(8) lgkmcnt(0)
	s_setprio 1
	s_barrier
	v_mfma_f32_16x16x32_bf16 v[60:63], v[148:151], v[192:195], v[60:63]
	v_mfma_f32_16x16x32_bf16 v[56:59], v[156:159], v[192:195], v[56:59]
	v_mfma_f32_16x16x32_bf16 v[44:47], v[148:151], v[204:207], v[44:47]
	v_mfma_f32_16x16x32_bf16 v[40:43], v[156:159], v[204:207], v[40:43]
	v_mfma_f32_16x16x32_bf16 v[28:31], v[148:151], v[212:215], v[28:31]
	v_mfma_f32_16x16x32_bf16 v[24:27], v[156:159], v[212:215], v[24:27]
	v_mfma_f32_16x16x32_bf16 v[12:15], v[148:151], v[220:223], v[12:15]
	v_mfma_f32_16x16x32_bf16 v[8:11], v[156:159], v[220:223], v[8:11]
	v_mfma_f32_16x16x32_bf16 v[60:63], v[152:155], v[196:199], v[60:63]
	v_mfma_f32_16x16x32_bf16 v[56:59], v[160:163], v[196:199], v[56:59]
	v_mfma_f32_16x16x32_bf16 v[44:47], v[152:155], v[208:211], v[44:47]
	v_mfma_f32_16x16x32_bf16 v[40:43], v[160:163], v[208:211], v[40:43]
	v_mfma_f32_16x16x32_bf16 v[28:31], v[152:155], v[216:219], v[28:31]
	v_mfma_f32_16x16x32_bf16 v[24:27], v[160:163], v[216:219], v[24:27]
	v_mfma_f32_16x16x32_bf16 v[12:15], v[152:155], v[224:227], v[12:15]
	v_mfma_f32_16x16x32_bf16 v[8:11], v[160:163], v[224:227], v[8:11]
	s_setprio 0
	s_setprio 1
	v_mfma_f32_16x16x32_bf16 v[52:55], v[164:167], v[192:195], v[52:55]
	v_mfma_f32_16x16x32_bf16 v[48:51], v[184:187], v[192:195], v[48:51]
	v_mfma_f32_16x16x32_bf16 v[36:39], v[164:167], v[204:207], v[36:39]
	v_mfma_f32_16x16x32_bf16 v[32:35], v[184:187], v[204:207], v[32:35]
	v_mfma_f32_16x16x32_bf16 v[20:23], v[164:167], v[212:215], v[20:23]
	v_mfma_f32_16x16x32_bf16 v[16:19], v[184:187], v[212:215], v[16:19]
	v_mfma_f32_16x16x32_bf16 v[4:7], v[164:167], v[220:223], v[4:7]
	v_mfma_f32_16x16x32_bf16 v[0:3], v[184:187], v[220:223], v[0:3]
	v_mfma_f32_16x16x32_bf16 v[52:55], v[180:183], v[196:199], v[52:55]
	v_mfma_f32_16x16x32_bf16 v[48:51], v[188:191], v[196:199], v[48:51]
	v_mfma_f32_16x16x32_bf16 v[36:39], v[180:183], v[208:211], v[36:39]
	v_mfma_f32_16x16x32_bf16 v[32:35], v[188:191], v[208:211], v[32:35]
	v_mfma_f32_16x16x32_bf16 v[20:23], v[180:183], v[216:219], v[20:23]
	v_mfma_f32_16x16x32_bf16 v[16:19], v[188:191], v[216:219], v[16:19]
	v_mfma_f32_16x16x32_bf16 v[4:7], v[180:183], v[224:227], v[4:7]
	v_mfma_f32_16x16x32_bf16 v[0:3], v[188:191], v[224:227], v[0:3]
	s_setprio 0
	s_add_i32 s66, s66, 2
	s_add_u32 s50, s50, 0x100
	s_addc_u32 s51, s51, 0
	s_add_u32 s43, s43, 0x100
	s_addc_u32 s45, s45, 0
	s_cmp_gt_u32 s66, 13
	s_barrier
	s_cbranch_scc0 .LBB0_220
	s_and_b64 vcc, exec, s[24:25]
	s_cbranch_vccz .LBB0_223
	s_barrier

.LBB0_401:
	ds_read_b128 v[128:131], v189
	ds_read_b128 v[132:135], v189 offset:1024
	ds_read_b128 v[136:139], v189 offset:2048
	ds_read_b128 v[140:143], v189 offset:3072
	ds_read_b128 v[144:147], v190
	ds_read_b128 v[148:151], v190 offset:1024
	ds_read_b128 v[168:171], v190 offset:2048
	ds_read_b128 v[172:175], v190 offset:3072
	s_add_u32 s4, s42, 0xfff80080
	s_addc_u32 s5, s43, -1
	s_cmp_eq_u32 s59, 28
	s_cselect_b32 s45, s35, s5
	s_cselect_b32 s44, s41, s4
	s_cselect_b32 s5, s31, s58
	s_cselect_b32 s4, s56, s57
	v_lshl_add_u64 v[184:185], s[42:43], 0, v[160:161]
	s_add_i32 m0, s47, 0xc000
	ds_read_b128 v[176:179], v191
	ds_read_b128 v[180:183], v191 offset:1024
	ds_read_b128 v[194:197], v191 offset:2048
	ds_read_b128 v[198:201], v191 offset:3072
	ds_read_b128 v[204:207], v191 offset:4096
	ds_read_b128 v[208:211], v191 offset:5120
	ds_read_b128 v[212:215], v191 offset:6144
	ds_read_b128 v[216:219], v191 offset:7168
	global_load_lds_dwordx4 v[184:185], off
	s_add_i32 m0, s47, 0xe000
	v_lshl_add_u64 v[184:185], s[42:43], 0, v[162:163]
	global_load_lds_dwordx4 v[184:185], off
	s_waitcnt vmcnt(8) lgkmcnt(0)
	s_setprio 1
	s_barrier
	v_mfma_f32_16x16x32_bf16 v[124:127], v[128:131], v[176:179], v[124:127]
	v_mfma_f32_16x16x32_bf16 v[120:123], v[136:139], v[176:179], v[120:123]
	v_mfma_f32_16x16x32_bf16 v[108:111], v[128:131], v[194:197], v[108:111]
	v_mfma_f32_16x16x32_bf16 v[104:107], v[136:139], v[194:197], v[104:107]
	v_mfma_f32_16x16x32_bf16 v[92:95], v[128:131], v[204:207], v[92:95]
	v_mfma_f32_16x16x32_bf16 v[88:91], v[136:139], v[204:207], v[88:91]
	v_mfma_f32_16x16x32_bf16 v[76:79], v[128:131], v[212:215], v[76:79]
	v_mfma_f32_16x16x32_bf16 v[72:75], v[136:139], v[212:215], v[72:75]
	v_mfma_f32_16x16x32_bf16 v[124:127], v[132:135], v[180:183], v[124:127]
	v_mfma_f32_16x16x32_bf16 v[120:123], v[140:143], v[180:183], v[120:123]
	v_mfma_f32_16x16x32_bf16 v[108:111], v[132:135], v[198:201], v[108:111]
	v_mfma_f32_16x16x32_bf16 v[104:107], v[140:143], v[198:201], v[104:107]
	v_mfma_f32_16x16x32_bf16 v[92:95], v[132:135], v[208:211], v[92:95]
	v_mfma_f32_16x16x32_bf16 v[88:91], v[140:143], v[208:211], v[88:91]
	v_mfma_f32_16x16x32_bf16 v[76:79], v[132:135], v[216:219], v[76:79]
	v_mfma_f32_16x16x32_bf16 v[72:75], v[140:143], v[216:219], v[72:75]
	s_setprio 0
	s_setprio 1
	v_mfma_f32_16x16x32_bf16 v[116:119], v[144:147], v[176:179], v[116:119]
	v_mfma_f32_16x16x32_bf16 v[112:115], v[168:171], v[176:179], v[112:115]
	v_mfma_f32_16x16x32_bf16 v[100:103], v[144:147], v[194:197], v[100:103]
	v_mfma_f32_16x16x32_bf16 v[96:99], v[168:171], v[194:197], v[96:99]
	v_mfma_f32_16x16x32_bf16 v[84:87], v[144:147], v[204:207], v[84:87]
	v_mfma_f32_16x16x32_bf16 v[80:83], v[168:171], v[204:207], v[80:83]
	v_mfma_f32_16x16x32_bf16 v[68:71], v[144:147], v[212:215], v[68:71]
	v_mfma_f32_16x16x32_bf16 v[64:67], v[168:171], v[212:215], v[64:67]
	v_mfma_f32_16x16x32_bf16 v[116:119], v[148:151], v[180:183], v[116:119]
	v_mfma_f32_16x16x32_bf16 v[112:115], v[172:175], v[180:183], v[112:115]
	v_mfma_f32_16x16x32_bf16 v[100:103], v[148:151], v[198:201], v[100:103]
	v_mfma_f32_16x16x32_bf16 v[96:99], v[172:175], v[198:201], v[96:99]
	v_mfma_f32_16x16x32_bf16 v[84:87], v[148:151], v[208:211], v[84:87]
	v_mfma_f32_16x16x32_bf16 v[80:83], v[172:175], v[208:211], v[80:83]
	v_mfma_f32_16x16x32_bf16 v[68:71], v[148:151], v[216:219], v[68:71]
	v_mfma_f32_16x16x32_bf16 v[64:67], v[172:175], v[216:219], v[64:67]
	s_setprio 0
	s_barrier
	s_add_i32 s60, s53, s46
	v_lshl_add_u64 v[184:185], s[4:5], 0, v[154:155]
	s_mov_b32 m0, s60
	ds_read_b128 v[176:179], v191 offset:16384
	ds_read_b128 v[180:183], v191 offset:17408
	ds_read_b128 v[194:197], v191 offset:18432
	ds_read_b128 v[198:201], v191 offset:19456
	ds_read_b128 v[204:207], v191 offset:20480
	ds_read_b128 v[208:211], v191 offset:21504
	ds_read_b128 v[212:215], v191 offset:22528
	ds_read_b128 v[216:219], v191 offset:23552
	global_load_lds_dwordx4 v[184:185], off
	s_add_i32 m0, s60, 0x2000
	s_add_u32 s60, s4, 0x80000
	v_lshl_add_u64 v[220:221], s[4:5], 0, v[158:159]
	s_addc_u32 s61, s5, 0
	s_add_i32 s62, s54, s46
	global_load_lds_dwordx4 v[220:221], off
	v_lshl_add_u64 v[222:223], s[60:61], 0, v[154:155]
	s_mov_b32 m0, s62
	v_lshl_add_u64 v[224:225], s[44:45], 0, v[156:157]
	global_load_lds_dwordx4 v[222:223], off
	s_add_i32 m0, s62, 0x2000
	v_lshl_add_u64 v[222:223], s[60:61], 0, v[158:159]
	global_load_lds_dwordx4 v[222:223], off
	s_mov_b32 m0, s47
	v_lshl_add_u64 v[222:223], s[44:45], 0, v[152:153]
	global_load_lds_dwordx4 v[222:223], off
	s_mov_b32 m0, s48
	s_nop 0
	global_load_lds_dwordx4 v[224:225], off
	s_waitcnt vmcnt(8) lgkmcnt(0)
	s_setprio 1
	s_barrier
	v_mfma_f32_16x16x32_bf16 v[60:63], v[128:131], v[176:179], v[60:63]
	v_mfma_f32_16x16x32_bf16 v[56:59], v[136:139], v[176:179], v[56:59]
	v_mfma_f32_16x16x32_bf16 v[44:47], v[128:131], v[194:197], v[44:47]
	v_mfma_f32_16x16x32_bf16 v[40:43], v[136:139], v[194:197], v[40:43]
	v_mfma_f32_16x16x32_bf16 v[28:31], v[128:131], v[204:207], v[28:31]
	v_mfma_f32_16x16x32_bf16 v[24:27], v[136:139], v[204:207], v[24:27]
	v_mfma_f32_16x16x32_bf16 v[12:15], v[128:131], v[212:215], v[12:15]
	v_mfma_f32_16x16x32_bf16 v[8:11], v[136:139], v[212:215], v[8:11]
	v_mfma_f32_16x16x32_bf16 v[60:63], v[132:135], v[180:183], v[60:63]
	v_mfma_f32_16x16x32_bf16 v[56:59], v[140:143], v[180:183], v[56:59]
	v_mfma_f32_16x16x32_bf16 v[44:47], v[132:135], v[198:201], v[44:47]
	v_mfma_f32_16x16x32_bf16 v[40:43], v[140:143], v[198:201], v[40:43]
	v_mfma_f32_16x16x32_bf16 v[28:31], v[132:135], v[208:211], v[28:31]
	v_mfma_f32_16x16x32_bf16 v[24:27], v[140:143], v[208:211], v[24:27]
	v_mfma_f32_16x16x32_bf16 v[12:15], v[132:135], v[216:219], v[12:15]
	v_mfma_f32_16x16x32_bf16 v[8:11], v[140:143], v[216:219], v[8:11]
	s_setprio 0
	s_setprio 1
	v_mfma_f32_16x16x32_bf16 v[52:55], v[144:147], v[176:179], v[52:55]
	v_mfma_f32_16x16x32_bf16 v[48:51], v[168:171], v[176:179], v[48:51]
	v_mfma_f32_16x16x32_bf16 v[36:39], v[144:147], v[194:197], v[36:39]
	v_mfma_f32_16x16x32_bf16 v[32:35], v[168:171], v[194:197], v[32:35]
	v_mfma_f32_16x16x32_bf16 v[20:23], v[144:147], v[204:207], v[20:23]
	v_mfma_f32_16x16x32_bf16 v[16:19], v[168:171], v[204:207], v[16:19]
	v_mfma_f32_16x16x32_bf16 v[4:7], v[144:147], v[212:215], v[4:7]
	v_mfma_f32_16x16x32_bf16 v[0:3], v[168:171], v[212:215], v[0:3]
	v_mfma_f32_16x16x32_bf16 v[52:55], v[148:151], v[180:183], v[52:55]
	v_mfma_f32_16x16x32_bf16 v[48:51], v[172:175], v[180:183], v[48:51]
	v_mfma_f32_16x16x32_bf16 v[36:39], v[148:151], v[198:201], v[36:39]
	v_mfma_f32_16x16x32_bf16 v[32:35], v[172:175], v[198:201], v[32:35]
	v_mfma_f32_16x16x32_bf16 v[20:23], v[148:151], v[208:211], v[20:23]
	v_mfma_f32_16x16x32_bf16 v[16:19], v[172:175], v[208:211], v[16:19]
	v_mfma_f32_16x16x32_bf16 v[4:7], v[148:151], v[216:219], v[4:7]
	v_mfma_f32_16x16x32_bf16 v[0:3], v[172:175], v[216:219], v[0:3]
	s_setprio 0
	s_barrier
	s_add_i32 s60, 0, 0x18000
	s_add_i32 s61, 0, 0x1c000
	v_add_u32_e32 v140, s60, v187
	v_add_u32_e32 v172, s61, v187
	ds_read_b128 v[128:131], v140
	ds_read_b128 v[132:135], v140 offset:1024
	ds_read_b128 v[136:139], v140 offset:2048
	ds_read_b128 v[140:143], v140 offset:3072
	ds_read_b128 v[144:147], v172
	ds_read_b128 v[148:151], v172 offset:1024
	ds_read_b128 v[168:171], v172 offset:2048
	ds_read_b128 v[172:175], v172 offset:3072
	s_add_u32 s44, s44, 0x80000
	s_addc_u32 s45, s45, 0
	s_mov_b32 m0, s49
	v_lshl_add_u64 v[226:227], s[44:45], 0, v[152:153]
	ds_read_b128 v[176:179], v191 offset:32768
	ds_read_b128 v[180:183], v191 offset:33792
	ds_read_b128 v[194:197], v191 offset:34816
	ds_read_b128 v[198:201], v191 offset:35840
	ds_read_b128 v[204:207], v191 offset:36864
	ds_read_b128 v[208:211], v191 offset:37888
	ds_read_b128 v[212:215], v191 offset:38912
	ds_read_b128 v[216:219], v191 offset:39936
	global_load_lds_dwordx4 v[226:227], off
	s_mov_b32 m0, s50
	v_lshl_add_u64 v[226:227], s[44:45], 0, v[156:157]
	global_load_lds_dwordx4 v[226:227], off
	s_waitcnt vmcnt(8) lgkmcnt(0)
	s_setprio 1
	s_barrier
	v_mfma_f32_16x16x32_bf16 v[124:127], v[128:131], v[176:179], v[124:127]
	v_mfma_f32_16x16x32_bf16 v[120:123], v[136:139], v[176:179], v[120:123]
	v_mfma_f32_16x16x32_bf16 v[108:111], v[128:131], v[194:197], v[108:111]
	v_mfma_f32_16x16x32_bf16 v[104:107], v[136:139], v[194:197], v[104:107]
	v_mfma_f32_16x16x32_bf16 v[92:95], v[128:131], v[204:207], v[92:95]
	v_mfma_f32_16x16x32_bf16 v[88:91], v[136:139], v[204:207], v[88:91]
	v_mfma_f32_16x16x32_bf16 v[76:79], v[128:131], v[212:215], v[76:79]
	v_mfma_f32_16x16x32_bf16 v[72:75], v[136:139], v[212:215], v[72:75]
	v_mfma_f32_16x16x32_bf16 v[124:127], v[132:135], v[180:183], v[124:127]
	v_mfma_f32_16x16x32_bf16 v[120:123], v[140:143], v[180:183], v[120:123]
	v_mfma_f32_16x16x32_bf16 v[108:111], v[132:135], v[198:201], v[108:111]
	v_mfma_f32_16x16x32_bf16 v[104:107], v[140:143], v[198:201], v[104:107]
	v_mfma_f32_16x16x32_bf16 v[92:95], v[132:135], v[208:211], v[92:95]
	v_mfma_f32_16x16x32_bf16 v[88:91], v[140:143], v[208:211], v[88:91]
	v_mfma_f32_16x16x32_bf16 v[76:79], v[132:135], v[216:219], v[76:79]
	v_mfma_f32_16x16x32_bf16 v[72:75], v[140:143], v[216:219], v[72:75]
	s_setprio 0
	s_setprio 1
	v_mfma_f32_16x16x32_bf16 v[116:119], v[144:147], v[176:179], v[116:119]
	v_mfma_f32_16x16x32_bf16 v[112:115], v[168:171], v[176:179], v[112:115]
	v_mfma_f32_16x16x32_bf16 v[100:103], v[144:147], v[194:197], v[100:103]
	v_mfma_f32_16x16x32_bf16 v[96:99], v[168:171], v[194:197], v[96:99]
	v_mfma_f32_16x16x32_bf16 v[84:87], v[144:147], v[204:207], v[84:87]
	v_mfma_f32_16x16x32_bf16 v[80:83], v[168:171], v[204:207], v[80:83]
	v_mfma_f32_16x16x32_bf16 v[68:71], v[144:147], v[212:215], v[68:71]
	v_mfma_f32_16x16x32_bf16 v[64:67], v[168:171], v[212:215], v[64:67]
	v_mfma_f32_16x16x32_bf16 v[116:119], v[148:151], v[180:183], v[116:119]
	v_mfma_f32_16x16x32_bf16 v[112:115], v[172:175], v[180:183], v[112:115]
	v_mfma_f32_16x16x32_bf16 v[100:103], v[148:151], v[198:201], v[100:103]
	v_mfma_f32_16x16x32_bf16 v[96:99], v[172:175], v[198:201], v[96:99]
	v_mfma_f32_16x16x32_bf16 v[84:87], v[148:151], v[208:211], v[84:87]
	v_mfma_f32_16x16x32_bf16 v[80:83], v[172:175], v[208:211], v[80:83]
	v_mfma_f32_16x16x32_bf16 v[68:71], v[148:151], v[216:219], v[68:71]
	v_mfma_f32_16x16x32_bf16 v[64:67], v[172:175], v[216:219], v[64:67]
	s_setprio 0
	s_barrier
	s_add_i32 s44, s60, s46
	v_lshl_add_u64 v[184:185], v[184:185], 0, s[26:27]
	s_mov_b32 m0, s44
	ds_read_b128 v[176:179], v191 offset:49152
	ds_read_b128 v[180:183], v191 offset:50176
	ds_read_b128 v[194:197], v191 offset:51200
	ds_read_b128 v[198:201], v191 offset:52224
	ds_read_b128 v[204:207], v191 offset:53248
	ds_read_b128 v[208:211], v191 offset:54272
	ds_read_b128 v[212:215], v191 offset:55296
	ds_read_b128 v[216:219], v191 offset:56320
	global_load_lds_dwordx4 v[184:185], off
	s_add_i32 m0, s44, 0x2000
	s_add_u32 s4, s4, 0x80080
	v_lshl_add_u64 v[184:185], v[220:221], 0, s[26:27]
	s_addc_u32 s5, s5, 0
	s_add_i32 s44, s61, s46
	global_load_lds_dwordx4 v[184:185], off
	s_mov_b32 m0, s44
	v_lshl_add_u64 v[184:185], s[4:5], 0, v[154:155]
	global_load_lds_dwordx4 v[184:185], off
	s_add_i32 m0, s44, 0x2000
	v_lshl_add_u64 v[184:185], s[4:5], 0, v[158:159]
	global_load_lds_dwordx4 v[184:185], off
	s_mov_b32 m0, s33
	v_lshl_add_u64 v[184:185], v[222:223], 0, s[26:27]
	global_load_lds_dwordx4 v[184:185], off
	s_mov_b32 m0, s52
	v_lshl_add_u64 v[184:185], v[224:225], 0, s[26:27]
	global_load_lds_dwordx4 v[184:185], off
	s_waitcnt vmcnt(8) lgkmcnt(0)
	s_setprio 1
	s_barrier
	v_mfma_f32_16x16x32_bf16 v[60:63], v[128:131], v[176:179], v[60:63]
	v_mfma_f32_16x16x32_bf16 v[56:59], v[136:139], v[176:179], v[56:59]
	v_mfma_f32_16x16x32_bf16 v[44:47], v[128:131], v[194:197], v[44:47]
	v_mfma_f32_16x16x32_bf16 v[40:43], v[136:139], v[194:197], v[40:43]
	v_mfma_f32_16x16x32_bf16 v[28:31], v[128:131], v[204:207], v[28:31]
	v_mfma_f32_16x16x32_bf16 v[24:27], v[136:139], v[204:207], v[24:27]
	v_mfma_f32_16x16x32_bf16 v[12:15], v[128:131], v[212:215], v[12:15]
	v_mfma_f32_16x16x32_bf16 v[8:11], v[136:139], v[212:215], v[8:11]
	v_mfma_f32_16x16x32_bf16 v[60:63], v[132:135], v[180:183], v[60:63]
	v_mfma_f32_16x16x32_bf16 v[56:59], v[140:143], v[180:183], v[56:59]
	v_mfma_f32_16x16x32_bf16 v[44:47], v[132:135], v[198:201], v[44:47]
	v_mfma_f32_16x16x32_bf16 v[40:43], v[140:143], v[198:201], v[40:43]
	v_mfma_f32_16x16x32_bf16 v[28:31], v[132:135], v[208:211], v[28:31]
	v_mfma_f32_16x16x32_bf16 v[24:27], v[140:143], v[208:211], v[24:27]
	v_mfma_f32_16x16x32_bf16 v[12:15], v[132:135], v[216:219], v[12:15]
	v_mfma_f32_16x16x32_bf16 v[8:11], v[140:143], v[216:219], v[8:11]
	s_setprio 0
	s_setprio 1
	v_mfma_f32_16x16x32_bf16 v[52:55], v[144:147], v[176:179], v[52:55]
	v_mfma_f32_16x16x32_bf16 v[48:51], v[168:171], v[176:179], v[48:51]
	v_mfma_f32_16x16x32_bf16 v[36:39], v[144:147], v[194:197], v[36:39]
	v_mfma_f32_16x16x32_bf16 v[32:35], v[168:171], v[194:197], v[32:35]
	v_mfma_f32_16x16x32_bf16 v[20:23], v[144:147], v[204:207], v[20:23]
	v_mfma_f32_16x16x32_bf16 v[16:19], v[168:171], v[204:207], v[16:19]
	v_mfma_f32_16x16x32_bf16 v[4:7], v[144:147], v[212:215], v[4:7]
	v_mfma_f32_16x16x32_bf16 v[0:3], v[168:171], v[212:215], v[0:3]
	v_mfma_f32_16x16x32_bf16 v[52:55], v[148:151], v[180:183], v[52:55]
	v_mfma_f32_16x16x32_bf16 v[48:51], v[172:175], v[180:183], v[48:51]
	v_mfma_f32_16x16x32_bf16 v[36:39], v[148:151], v[198:201], v[36:39]
	v_mfma_f32_16x16x32_bf16 v[32:35], v[172:175], v[198:201], v[32:35]
	v_mfma_f32_16x16x32_bf16 v[20:23], v[148:151], v[208:211], v[20:23]
	v_mfma_f32_16x16x32_bf16 v[16:19], v[172:175], v[208:211], v[16:19]
	v_mfma_f32_16x16x32_bf16 v[4:7], v[148:151], v[216:219], v[4:7]
	v_mfma_f32_16x16x32_bf16 v[0:3], v[172:175], v[216:219], v[0:3]
	s_setprio 0
	s_add_i32 s59, s59, 2
	s_add_u32 s42, s42, 0x100
	s_addc_u32 s43, s43, 0
	s_add_u32 s57, s57, 0x100
	s_addc_u32 s58, s58, 0
	s_cmp_gt_u32 s59, 29
	s_barrier
	s_cbranch_scc0 .LBB0_401
	s_and_b64 vcc, exec, s[28:29]
	s_cbranch_vccz .LBB0_404
	s_barrier

.LBB0_483:
	ds_read_b128 v[146:149], v169
	ds_read_b128 v[150:153], v169 offset:1024
	ds_read_b128 v[154:157], v169 offset:2048
	ds_read_b128 v[160:163], v169 offset:3072
	ds_read_b128 v[180:183], v171
	ds_read_b128 v[184:187], v171 offset:1024
	ds_read_b128 v[188:191], v171 offset:2048
	ds_read_b128 v[192:195], v171 offset:3072
	s_add_u32 s4, s10, 0xfffc0080
	s_addc_u32 s5, s11, -1
	s_cmp_eq_u32 s56, 12
	s_cselect_b32 s13, s9, s5
	s_cselect_b32 s12, s37, s4
	s_cselect_b32 s5, s35, s55
	s_cselect_b32 s4, s53, s54
	v_lshl_add_u64 v[200:201], s[10:11], 0, v[138:139]
	s_add_i32 m0, s42, 0xc000
	ds_read_b128 v[196:199], v173
	ds_read_b128 v[204:207], v173 offset:1024
	ds_read_b128 v[208:211], v173 offset:2048
	ds_read_b128 v[212:215], v173 offset:3072
	ds_read_b128 v[216:219], v173 offset:4096
	ds_read_b128 v[220:223], v173 offset:5120
	ds_read_b128 v[224:227], v173 offset:6144
	ds_read_b128 v[228:231], v173 offset:7168
	global_load_lds_dwordx4 v[200:201], off
	s_add_i32 m0, s42, 0xe000
	v_lshl_add_u64 v[200:201], s[10:11], 0, v[140:141]
	global_load_lds_dwordx4 v[200:201], off
	s_waitcnt vmcnt(8) lgkmcnt(0)
	s_setprio 1
	s_barrier
	v_mfma_f32_16x16x32_bf16 v[124:127], v[146:149], v[196:199], v[124:127]
	v_mfma_f32_16x16x32_bf16 v[116:119], v[154:157], v[196:199], v[116:119]
	v_mfma_f32_16x16x32_bf16 v[108:111], v[146:149], v[208:211], v[108:111]
	v_mfma_f32_16x16x32_bf16 v[100:103], v[154:157], v[208:211], v[100:103]
	v_mfma_f32_16x16x32_bf16 v[92:95], v[146:149], v[216:219], v[92:95]
	v_mfma_f32_16x16x32_bf16 v[84:87], v[154:157], v[216:219], v[84:87]
	v_mfma_f32_16x16x32_bf16 v[76:79], v[146:149], v[224:227], v[76:79]
	v_mfma_f32_16x16x32_bf16 v[68:71], v[154:157], v[224:227], v[68:71]
	v_mfma_f32_16x16x32_bf16 v[124:127], v[150:153], v[204:207], v[124:127]
	v_mfma_f32_16x16x32_bf16 v[116:119], v[160:163], v[204:207], v[116:119]
	v_mfma_f32_16x16x32_bf16 v[108:111], v[150:153], v[212:215], v[108:111]
	v_mfma_f32_16x16x32_bf16 v[100:103], v[160:163], v[212:215], v[100:103]
	v_mfma_f32_16x16x32_bf16 v[92:95], v[150:153], v[220:223], v[92:95]
	v_mfma_f32_16x16x32_bf16 v[84:87], v[160:163], v[220:223], v[84:87]
	v_mfma_f32_16x16x32_bf16 v[76:79], v[150:153], v[228:231], v[76:79]
	v_mfma_f32_16x16x32_bf16 v[68:71], v[160:163], v[228:231], v[68:71]
	s_setprio 0
	s_setprio 1
	v_mfma_f32_16x16x32_bf16 v[120:123], v[180:183], v[196:199], v[120:123]
	v_mfma_f32_16x16x32_bf16 v[112:115], v[188:191], v[196:199], v[112:115]
	v_mfma_f32_16x16x32_bf16 v[104:107], v[180:183], v[208:211], v[104:107]
	v_mfma_f32_16x16x32_bf16 v[96:99], v[188:191], v[208:211], v[96:99]
	v_mfma_f32_16x16x32_bf16 v[88:91], v[180:183], v[216:219], v[88:91]
	v_mfma_f32_16x16x32_bf16 v[80:83], v[188:191], v[216:219], v[80:83]
	v_mfma_f32_16x16x32_bf16 v[72:75], v[180:183], v[224:227], v[72:75]
	v_mfma_f32_16x16x32_bf16 v[64:67], v[188:191], v[224:227], v[64:67]
	v_mfma_f32_16x16x32_bf16 v[120:123], v[184:187], v[204:207], v[120:123]
	v_mfma_f32_16x16x32_bf16 v[112:115], v[192:195], v[204:207], v[112:115]
	v_mfma_f32_16x16x32_bf16 v[104:107], v[184:187], v[212:215], v[104:107]
	v_mfma_f32_16x16x32_bf16 v[96:99], v[192:195], v[212:215], v[96:99]
	v_mfma_f32_16x16x32_bf16 v[88:91], v[184:187], v[220:223], v[88:91]
	v_mfma_f32_16x16x32_bf16 v[80:83], v[192:195], v[220:223], v[80:83]
	v_mfma_f32_16x16x32_bf16 v[72:75], v[184:187], v[228:231], v[72:75]
	v_mfma_f32_16x16x32_bf16 v[64:67], v[192:195], v[228:231], v[64:67]
	s_setprio 0
	s_barrier
	s_add_i32 s57, s49, s23
	v_lshl_add_u64 v[200:201], s[4:5], 0, v[132:133]
	s_mov_b32 m0, s57
	ds_read_b128 v[196:199], v173 offset:16384
	ds_read_b128 v[204:207], v173 offset:17408
	ds_read_b128 v[208:211], v173 offset:18432
	ds_read_b128 v[212:215], v173 offset:19456
	ds_read_b128 v[216:219], v173 offset:20480
	ds_read_b128 v[220:223], v173 offset:21504
	ds_read_b128 v[224:227], v173 offset:22528
	ds_read_b128 v[228:231], v173 offset:23552
	global_load_lds_dwordx4 v[200:201], off
	s_add_i32 m0, s57, 0x2000
	s_add_u32 s58, s4, 0x40000
	v_lshl_add_u64 v[232:233], s[4:5], 0, v[128:129]
	s_addc_u32 s59, s5, 0
	s_add_i32 s57, s50, s23
	global_load_lds_dwordx4 v[232:233], off
	v_lshl_add_u64 v[234:235], s[58:59], 0, v[132:133]
	s_mov_b32 m0, s57
	v_lshl_add_u64 v[236:237], s[12:13], 0, v[130:131]
	global_load_lds_dwordx4 v[234:235], off
	s_add_i32 m0, s57, 0x2000
	v_lshl_add_u64 v[234:235], s[58:59], 0, v[128:129]
	global_load_lds_dwordx4 v[234:235], off
	s_mov_b32 m0, s42
	v_lshl_add_u64 v[234:235], s[12:13], 0, v[134:135]
	global_load_lds_dwordx4 v[234:235], off
	s_mov_b32 m0, s43
	s_nop 0
	global_load_lds_dwordx4 v[236:237], off
	s_waitcnt vmcnt(8) lgkmcnt(0)
	s_setprio 1
	s_barrier
	v_mfma_f32_16x16x32_bf16 v[60:63], v[146:149], v[196:199], v[60:63]
	v_mfma_f32_16x16x32_bf16 v[52:55], v[154:157], v[196:199], v[52:55]
	v_mfma_f32_16x16x32_bf16 v[44:47], v[146:149], v[208:211], v[44:47]
	v_mfma_f32_16x16x32_bf16 v[36:39], v[154:157], v[208:211], v[36:39]
	v_mfma_f32_16x16x32_bf16 v[28:31], v[146:149], v[216:219], v[28:31]
	v_mfma_f32_16x16x32_bf16 v[20:23], v[154:157], v[216:219], v[20:23]
	v_mfma_f32_16x16x32_bf16 v[12:15], v[146:149], v[224:227], v[12:15]
	v_mfma_f32_16x16x32_bf16 v[4:7], v[154:157], v[224:227], v[4:7]
	v_mfma_f32_16x16x32_bf16 v[60:63], v[150:153], v[204:207], v[60:63]
	v_mfma_f32_16x16x32_bf16 v[52:55], v[160:163], v[204:207], v[52:55]
	v_mfma_f32_16x16x32_bf16 v[44:47], v[150:153], v[212:215], v[44:47]
	v_mfma_f32_16x16x32_bf16 v[36:39], v[160:163], v[212:215], v[36:39]
	v_mfma_f32_16x16x32_bf16 v[28:31], v[150:153], v[220:223], v[28:31]
	v_mfma_f32_16x16x32_bf16 v[20:23], v[160:163], v[220:223], v[20:23]
	v_mfma_f32_16x16x32_bf16 v[12:15], v[150:153], v[228:231], v[12:15]
	v_mfma_f32_16x16x32_bf16 v[4:7], v[160:163], v[228:231], v[4:7]
	s_setprio 0
	s_setprio 1
	v_mfma_f32_16x16x32_bf16 v[56:59], v[180:183], v[196:199], v[56:59]
	v_mfma_f32_16x16x32_bf16 v[48:51], v[188:191], v[196:199], v[48:51]
	v_mfma_f32_16x16x32_bf16 v[40:43], v[180:183], v[208:211], v[40:43]
	v_mfma_f32_16x16x32_bf16 v[32:35], v[188:191], v[208:211], v[32:35]
	v_mfma_f32_16x16x32_bf16 v[24:27], v[180:183], v[216:219], v[24:27]
	v_mfma_f32_16x16x32_bf16 v[16:19], v[188:191], v[216:219], v[16:19]
	v_mfma_f32_16x16x32_bf16 v[8:11], v[180:183], v[224:227], v[8:11]
	v_mfma_f32_16x16x32_bf16 v[0:3], v[188:191], v[224:227], v[0:3]
	v_mfma_f32_16x16x32_bf16 v[56:59], v[184:187], v[204:207], v[56:59]
	v_mfma_f32_16x16x32_bf16 v[48:51], v[192:195], v[204:207], v[48:51]
	v_mfma_f32_16x16x32_bf16 v[40:43], v[184:187], v[212:215], v[40:43]
	v_mfma_f32_16x16x32_bf16 v[32:35], v[192:195], v[212:215], v[32:35]
	v_mfma_f32_16x16x32_bf16 v[24:27], v[184:187], v[220:223], v[24:27]
	v_mfma_f32_16x16x32_bf16 v[16:19], v[192:195], v[220:223], v[16:19]
	v_mfma_f32_16x16x32_bf16 v[8:11], v[184:187], v[228:231], v[8:11]
	v_mfma_f32_16x16x32_bf16 v[0:3], v[192:195], v[228:231], v[0:3]
	s_setprio 0
	s_barrier
	s_add_i32 s57, 0, 0x18000
	v_add_u32_e32 v158, s57, v165
	s_add_i32 s58, 0, 0x1c000
	ds_read_b128 v[146:149], v158
	ds_read_b128 v[150:153], v158 offset:1024
	ds_read_b128 v[154:157], v158 offset:2048
	ds_read_b128 v[160:163], v158 offset:3072
	v_add_u32_e32 v158, s58, v165
	ds_read_b128 v[180:183], v158
	ds_read_b128 v[184:187], v158 offset:1024
	ds_read_b128 v[188:191], v158 offset:2048
	ds_read_b128 v[192:195], v158 offset:3072
	s_add_u32 s12, s12, 0x40000
	s_addc_u32 s13, s13, 0
	s_mov_b32 m0, s44
	v_lshl_add_u64 v[238:239], s[12:13], 0, v[134:135]
	ds_read_b128 v[196:199], v173 offset:32768
	ds_read_b128 v[204:207], v173 offset:33792
	ds_read_b128 v[208:211], v173 offset:34816
	ds_read_b128 v[212:215], v173 offset:35840
	ds_read_b128 v[216:219], v173 offset:36864
	ds_read_b128 v[220:223], v173 offset:37888
	ds_read_b128 v[224:227], v173 offset:38912
	ds_read_b128 v[228:231], v173 offset:39936
	global_load_lds_dwordx4 v[238:239], off
	s_mov_b32 m0, s45
	v_lshl_add_u64 v[238:239], s[12:13], 0, v[130:131]
	global_load_lds_dwordx4 v[238:239], off
	s_waitcnt vmcnt(8) lgkmcnt(0)
	s_setprio 1
	s_barrier
	v_mfma_f32_16x16x32_bf16 v[124:127], v[146:149], v[196:199], v[124:127]
	v_mfma_f32_16x16x32_bf16 v[116:119], v[154:157], v[196:199], v[116:119]
	v_mfma_f32_16x16x32_bf16 v[108:111], v[146:149], v[208:211], v[108:111]
	v_mfma_f32_16x16x32_bf16 v[100:103], v[154:157], v[208:211], v[100:103]
	v_mfma_f32_16x16x32_bf16 v[92:95], v[146:149], v[216:219], v[92:95]
	v_mfma_f32_16x16x32_bf16 v[84:87], v[154:157], v[216:219], v[84:87]
	v_mfma_f32_16x16x32_bf16 v[76:79], v[146:149], v[224:227], v[76:79]
	v_mfma_f32_16x16x32_bf16 v[68:71], v[154:157], v[224:227], v[68:71]
	v_mfma_f32_16x16x32_bf16 v[124:127], v[150:153], v[204:207], v[124:127]
	v_mfma_f32_16x16x32_bf16 v[116:119], v[160:163], v[204:207], v[116:119]
	v_mfma_f32_16x16x32_bf16 v[108:111], v[150:153], v[212:215], v[108:111]
	v_mfma_f32_16x16x32_bf16 v[100:103], v[160:163], v[212:215], v[100:103]
	v_mfma_f32_16x16x32_bf16 v[92:95], v[150:153], v[220:223], v[92:95]
	v_mfma_f32_16x16x32_bf16 v[84:87], v[160:163], v[220:223], v[84:87]
	v_mfma_f32_16x16x32_bf16 v[76:79], v[150:153], v[228:231], v[76:79]
	v_mfma_f32_16x16x32_bf16 v[68:71], v[160:163], v[228:231], v[68:71]
	s_setprio 0
	s_setprio 1
	v_mfma_f32_16x16x32_bf16 v[120:123], v[180:183], v[196:199], v[120:123]
	v_mfma_f32_16x16x32_bf16 v[112:115], v[188:191], v[196:199], v[112:115]
	v_mfma_f32_16x16x32_bf16 v[104:107], v[180:183], v[208:211], v[104:107]
	v_mfma_f32_16x16x32_bf16 v[96:99], v[188:191], v[208:211], v[96:99]
	v_mfma_f32_16x16x32_bf16 v[88:91], v[180:183], v[216:219], v[88:91]
	v_mfma_f32_16x16x32_bf16 v[80:83], v[188:191], v[216:219], v[80:83]
	v_mfma_f32_16x16x32_bf16 v[72:75], v[180:183], v[224:227], v[72:75]
	v_mfma_f32_16x16x32_bf16 v[64:67], v[188:191], v[224:227], v[64:67]
	v_mfma_f32_16x16x32_bf16 v[120:123], v[184:187], v[204:207], v[120:123]
	v_mfma_f32_16x16x32_bf16 v[112:115], v[192:195], v[204:207], v[112:115]
	v_mfma_f32_16x16x32_bf16 v[104:107], v[184:187], v[212:215], v[104:107]
	v_mfma_f32_16x16x32_bf16 v[96:99], v[192:195], v[212:215], v[96:99]
	v_mfma_f32_16x16x32_bf16 v[88:91], v[184:187], v[220:223], v[88:91]
	v_mfma_f32_16x16x32_bf16 v[80:83], v[192:195], v[220:223], v[80:83]
	v_mfma_f32_16x16x32_bf16 v[72:75], v[184:187], v[228:231], v[72:75]
	v_mfma_f32_16x16x32_bf16 v[64:67], v[192:195], v[228:231], v[64:67]
	s_setprio 0
	s_barrier
	s_add_i32 s12, s57, s23
	v_lshl_add_u64 v[200:201], v[200:201], 0, s[28:29]
	s_mov_b32 m0, s12
	ds_read_b128 v[196:199], v173 offset:49152
	ds_read_b128 v[204:207], v173 offset:50176
	ds_read_b128 v[208:211], v173 offset:51200
	ds_read_b128 v[212:215], v173 offset:52224
	ds_read_b128 v[216:219], v173 offset:53248
	ds_read_b128 v[220:223], v173 offset:54272
	ds_read_b128 v[224:227], v173 offset:55296
	ds_read_b128 v[228:231], v173 offset:56320
	global_load_lds_dwordx4 v[200:201], off
	s_add_i32 m0, s12, 0x2000
	s_add_u32 s4, s4, 0x40080
	v_lshl_add_u64 v[200:201], v[232:233], 0, s[28:29]
	s_addc_u32 s5, s5, 0
	s_add_i32 s12, s58, s23
	global_load_lds_dwordx4 v[200:201], off
	s_mov_b32 m0, s12
	v_lshl_add_u64 v[200:201], s[4:5], 0, v[132:133]
	global_load_lds_dwordx4 v[200:201], off
	s_add_i32 m0, s12, 0x2000
	v_lshl_add_u64 v[200:201], s[4:5], 0, v[128:129]
	global_load_lds_dwordx4 v[200:201], off
	s_mov_b32 m0, s47
	v_lshl_add_u64 v[200:201], v[234:235], 0, s[28:29]
	global_load_lds_dwordx4 v[200:201], off
	s_mov_b32 m0, s48
	v_lshl_add_u64 v[200:201], v[236:237], 0, s[28:29]
	global_load_lds_dwordx4 v[200:201], off
	s_waitcnt vmcnt(8) lgkmcnt(0)
	s_setprio 1
	s_barrier
	v_mfma_f32_16x16x32_bf16 v[60:63], v[146:149], v[196:199], v[60:63]
	v_mfma_f32_16x16x32_bf16 v[52:55], v[154:157], v[196:199], v[52:55]
	v_mfma_f32_16x16x32_bf16 v[44:47], v[146:149], v[208:211], v[44:47]
	v_mfma_f32_16x16x32_bf16 v[36:39], v[154:157], v[208:211], v[36:39]
	v_mfma_f32_16x16x32_bf16 v[28:31], v[146:149], v[216:219], v[28:31]
	v_mfma_f32_16x16x32_bf16 v[20:23], v[154:157], v[216:219], v[20:23]
	v_mfma_f32_16x16x32_bf16 v[12:15], v[146:149], v[224:227], v[12:15]
	v_mfma_f32_16x16x32_bf16 v[4:7], v[154:157], v[224:227], v[4:7]
	v_mfma_f32_16x16x32_bf16 v[60:63], v[150:153], v[204:207], v[60:63]
	v_mfma_f32_16x16x32_bf16 v[52:55], v[160:163], v[204:207], v[52:55]
	v_mfma_f32_16x16x32_bf16 v[44:47], v[150:153], v[212:215], v[44:47]
	v_mfma_f32_16x16x32_bf16 v[36:39], v[160:163], v[212:215], v[36:39]
	v_mfma_f32_16x16x32_bf16 v[28:31], v[150:153], v[220:223], v[28:31]
	v_mfma_f32_16x16x32_bf16 v[20:23], v[160:163], v[220:223], v[20:23]
	v_mfma_f32_16x16x32_bf16 v[12:15], v[150:153], v[228:231], v[12:15]
	v_mfma_f32_16x16x32_bf16 v[4:7], v[160:163], v[228:231], v[4:7]
	s_setprio 0
	s_setprio 1
	v_mfma_f32_16x16x32_bf16 v[56:59], v[180:183], v[196:199], v[56:59]
	v_mfma_f32_16x16x32_bf16 v[48:51], v[188:191], v[196:199], v[48:51]
	v_mfma_f32_16x16x32_bf16 v[40:43], v[180:183], v[208:211], v[40:43]
	v_mfma_f32_16x16x32_bf16 v[32:35], v[188:191], v[208:211], v[32:35]
	v_mfma_f32_16x16x32_bf16 v[24:27], v[180:183], v[216:219], v[24:27]
	v_mfma_f32_16x16x32_bf16 v[16:19], v[188:191], v[216:219], v[16:19]
	v_mfma_f32_16x16x32_bf16 v[8:11], v[180:183], v[224:227], v[8:11]
	v_mfma_f32_16x16x32_bf16 v[0:3], v[188:191], v[224:227], v[0:3]
	v_mfma_f32_16x16x32_bf16 v[56:59], v[184:187], v[204:207], v[56:59]
	v_mfma_f32_16x16x32_bf16 v[48:51], v[192:195], v[204:207], v[48:51]
	v_mfma_f32_16x16x32_bf16 v[40:43], v[184:187], v[212:215], v[40:43]
	v_mfma_f32_16x16x32_bf16 v[32:35], v[192:195], v[212:215], v[32:35]
	v_mfma_f32_16x16x32_bf16 v[24:27], v[184:187], v[220:223], v[24:27]
	v_mfma_f32_16x16x32_bf16 v[16:19], v[192:195], v[220:223], v[16:19]
	v_mfma_f32_16x16x32_bf16 v[8:11], v[184:187], v[228:231], v[8:11]
	v_mfma_f32_16x16x32_bf16 v[0:3], v[192:195], v[228:231], v[0:3]
	s_setprio 0
	s_add_i32 s56, s56, 2
	s_add_u32 s10, s10, 0x100
	s_addc_u32 s11, s11, 0
	s_add_u32 s54, s54, 0x100
	s_addc_u32 s55, s55, 0
	s_cmp_gt_u32 s56, 13
	s_barrier
	s_cbranch_scc0 .LBB0_483
	s_and_b64 vcc, exec, s[30:31]
	s_cbranch_vccz .LBB0_486
	s_barrier

.LBB0_559:
	ds_read_b128 v[128:131], v189
	ds_read_b128 v[132:135], v189 offset:1024
	ds_read_b128 v[136:139], v189 offset:2048
	ds_read_b128 v[140:143], v189 offset:3072
	ds_read_b128 v[144:147], v190
	ds_read_b128 v[148:151], v190 offset:1024
	ds_read_b128 v[168:171], v190 offset:2048
	ds_read_b128 v[172:175], v190 offset:3072
	s_add_u32 s4, s22, 0x100
	s_addc_u32 s5, s23, 0
	s_cmp_eq_u32 s57, 40
	s_cselect_b32 s41, s11, s5
	s_cselect_b32 s40, s10, s4
	s_cselect_b32 s39, s37, s56
	s_cselect_b32 s38, s36, s55
	v_lshl_add_u64 v[184:185], s[22:23], 0, v[160:161]
	s_add_i32 m0, s43, 0xc000
	ds_read_b128 v[176:179], v191
	ds_read_b128 v[180:183], v191 offset:1024
	ds_read_b128 v[194:197], v191 offset:2048
	ds_read_b128 v[198:201], v191 offset:3072
	ds_read_b128 v[204:207], v191 offset:4096
	ds_read_b128 v[208:211], v191 offset:5120
	ds_read_b128 v[212:215], v191 offset:6144
	ds_read_b128 v[216:219], v191 offset:7168
	global_load_lds_dwordx4 v[184:185], off
	s_add_i32 m0, s43, 0xe000
	v_lshl_add_u64 v[184:185], s[22:23], 0, v[162:163]
	global_load_lds_dwordx4 v[184:185], off
	s_waitcnt vmcnt(8) lgkmcnt(0)
	s_setprio 1
	s_barrier
	v_mfma_f32_16x16x32_bf16 v[124:127], v[128:131], v[176:179], v[124:127]
	v_mfma_f32_16x16x32_bf16 v[120:123], v[136:139], v[176:179], v[120:123]
	v_mfma_f32_16x16x32_bf16 v[108:111], v[128:131], v[194:197], v[108:111]
	v_mfma_f32_16x16x32_bf16 v[104:107], v[136:139], v[194:197], v[104:107]
	v_mfma_f32_16x16x32_bf16 v[92:95], v[128:131], v[204:207], v[92:95]
	v_mfma_f32_16x16x32_bf16 v[88:91], v[136:139], v[204:207], v[88:91]
	v_mfma_f32_16x16x32_bf16 v[76:79], v[128:131], v[212:215], v[76:79]
	v_mfma_f32_16x16x32_bf16 v[72:75], v[136:139], v[212:215], v[72:75]
	v_mfma_f32_16x16x32_bf16 v[124:127], v[132:135], v[180:183], v[124:127]
	v_mfma_f32_16x16x32_bf16 v[120:123], v[140:143], v[180:183], v[120:123]
	v_mfma_f32_16x16x32_bf16 v[108:111], v[132:135], v[198:201], v[108:111]
	v_mfma_f32_16x16x32_bf16 v[104:107], v[140:143], v[198:201], v[104:107]
	v_mfma_f32_16x16x32_bf16 v[92:95], v[132:135], v[208:211], v[92:95]
	v_mfma_f32_16x16x32_bf16 v[88:91], v[140:143], v[208:211], v[88:91]
	v_mfma_f32_16x16x32_bf16 v[76:79], v[132:135], v[216:219], v[76:79]
	v_mfma_f32_16x16x32_bf16 v[72:75], v[140:143], v[216:219], v[72:75]
	s_setprio 0
	s_setprio 1
	v_mfma_f32_16x16x32_bf16 v[116:119], v[144:147], v[176:179], v[116:119]
	v_mfma_f32_16x16x32_bf16 v[112:115], v[168:171], v[176:179], v[112:115]
	v_mfma_f32_16x16x32_bf16 v[100:103], v[144:147], v[194:197], v[100:103]
	v_mfma_f32_16x16x32_bf16 v[96:99], v[168:171], v[194:197], v[96:99]
	v_mfma_f32_16x16x32_bf16 v[84:87], v[144:147], v[204:207], v[84:87]
	v_mfma_f32_16x16x32_bf16 v[80:83], v[168:171], v[204:207], v[80:83]
	v_mfma_f32_16x16x32_bf16 v[68:71], v[144:147], v[212:215], v[68:71]
	v_mfma_f32_16x16x32_bf16 v[64:67], v[168:171], v[212:215], v[64:67]
	v_mfma_f32_16x16x32_bf16 v[116:119], v[148:151], v[180:183], v[116:119]
	v_mfma_f32_16x16x32_bf16 v[112:115], v[172:175], v[180:183], v[112:115]
	v_mfma_f32_16x16x32_bf16 v[100:103], v[148:151], v[198:201], v[100:103]
	v_mfma_f32_16x16x32_bf16 v[96:99], v[172:175], v[198:201], v[96:99]
	v_mfma_f32_16x16x32_bf16 v[84:87], v[148:151], v[208:211], v[84:87]
	v_mfma_f32_16x16x32_bf16 v[80:83], v[172:175], v[208:211], v[80:83]
	v_mfma_f32_16x16x32_bf16 v[68:71], v[148:151], v[216:219], v[68:71]
	v_mfma_f32_16x16x32_bf16 v[64:67], v[172:175], v[216:219], v[64:67]
	s_setprio 0
	s_barrier
	s_add_i32 s22, s49, s42
	v_lshl_add_u64 v[184:185], s[38:39], 0, v[154:155]
	s_mov_b32 m0, s22
	ds_read_b128 v[176:179], v191 offset:16384
	ds_read_b128 v[180:183], v191 offset:17408
	ds_read_b128 v[194:197], v191 offset:18432
	ds_read_b128 v[198:201], v191 offset:19456
	ds_read_b128 v[204:207], v191 offset:20480
	ds_read_b128 v[208:211], v191 offset:21504
	ds_read_b128 v[212:215], v191 offset:22528
	ds_read_b128 v[216:219], v191 offset:23552
	global_load_lds_dwordx4 v[184:185], off
	s_add_i32 m0, s22, 0x2000
	s_add_u32 s22, s38, 0xb0000
	v_lshl_add_u64 v[220:221], s[38:39], 0, v[158:159]
	s_addc_u32 s23, s39, 0
	s_add_i32 s58, s50, s42
	global_load_lds_dwordx4 v[220:221], off
	v_lshl_add_u64 v[222:223], s[22:23], 0, v[154:155]
	s_mov_b32 m0, s58
	v_lshl_add_u64 v[224:225], s[40:41], 0, v[156:157]
	global_load_lds_dwordx4 v[222:223], off
	s_add_i32 m0, s58, 0x2000
	v_lshl_add_u64 v[222:223], s[22:23], 0, v[158:159]
	global_load_lds_dwordx4 v[222:223], off
	s_mov_b32 m0, s43
	v_lshl_add_u64 v[222:223], s[40:41], 0, v[152:153]
	global_load_lds_dwordx4 v[222:223], off
	s_mov_b32 m0, s44
	s_nop 0
	global_load_lds_dwordx4 v[224:225], off
	s_waitcnt vmcnt(8) lgkmcnt(0)
	s_setprio 1
	s_barrier
	v_mfma_f32_16x16x32_bf16 v[60:63], v[128:131], v[176:179], v[60:63]
	v_mfma_f32_16x16x32_bf16 v[56:59], v[136:139], v[176:179], v[56:59]
	v_mfma_f32_16x16x32_bf16 v[44:47], v[128:131], v[194:197], v[44:47]
	v_mfma_f32_16x16x32_bf16 v[40:43], v[136:139], v[194:197], v[40:43]
	v_mfma_f32_16x16x32_bf16 v[28:31], v[128:131], v[204:207], v[28:31]
	v_mfma_f32_16x16x32_bf16 v[24:27], v[136:139], v[204:207], v[24:27]
	v_mfma_f32_16x16x32_bf16 v[12:15], v[128:131], v[212:215], v[12:15]
	v_mfma_f32_16x16x32_bf16 v[8:11], v[136:139], v[212:215], v[8:11]
	v_mfma_f32_16x16x32_bf16 v[60:63], v[132:135], v[180:183], v[60:63]
	v_mfma_f32_16x16x32_bf16 v[56:59], v[140:143], v[180:183], v[56:59]
	v_mfma_f32_16x16x32_bf16 v[44:47], v[132:135], v[198:201], v[44:47]
	v_mfma_f32_16x16x32_bf16 v[40:43], v[140:143], v[198:201], v[40:43]
	v_mfma_f32_16x16x32_bf16 v[28:31], v[132:135], v[208:211], v[28:31]
	v_mfma_f32_16x16x32_bf16 v[24:27], v[140:143], v[208:211], v[24:27]
	v_mfma_f32_16x16x32_bf16 v[12:15], v[132:135], v[216:219], v[12:15]
	v_mfma_f32_16x16x32_bf16 v[8:11], v[140:143], v[216:219], v[8:11]
	s_setprio 0
	s_setprio 1
	v_mfma_f32_16x16x32_bf16 v[52:55], v[144:147], v[176:179], v[52:55]
	v_mfma_f32_16x16x32_bf16 v[48:51], v[168:171], v[176:179], v[48:51]
	v_mfma_f32_16x16x32_bf16 v[36:39], v[144:147], v[194:197], v[36:39]
	v_mfma_f32_16x16x32_bf16 v[32:35], v[168:171], v[194:197], v[32:35]
	v_mfma_f32_16x16x32_bf16 v[20:23], v[144:147], v[204:207], v[20:23]
	v_mfma_f32_16x16x32_bf16 v[16:19], v[168:171], v[204:207], v[16:19]
	v_mfma_f32_16x16x32_bf16 v[4:7], v[144:147], v[212:215], v[4:7]
	v_mfma_f32_16x16x32_bf16 v[0:3], v[168:171], v[212:215], v[0:3]
	v_mfma_f32_16x16x32_bf16 v[52:55], v[148:151], v[180:183], v[52:55]
	v_mfma_f32_16x16x32_bf16 v[48:51], v[172:175], v[180:183], v[48:51]
	v_mfma_f32_16x16x32_bf16 v[36:39], v[148:151], v[198:201], v[36:39]
	v_mfma_f32_16x16x32_bf16 v[32:35], v[172:175], v[198:201], v[32:35]
	v_mfma_f32_16x16x32_bf16 v[20:23], v[148:151], v[208:211], v[20:23]
	v_mfma_f32_16x16x32_bf16 v[16:19], v[172:175], v[208:211], v[16:19]
	v_mfma_f32_16x16x32_bf16 v[4:7], v[148:151], v[216:219], v[4:7]
	v_mfma_f32_16x16x32_bf16 v[0:3], v[172:175], v[216:219], v[0:3]
	s_setprio 0
	s_barrier
	s_add_i32 s58, 0, 0x18000
	s_add_i32 s59, 0, 0x1c000
	v_add_u32_e32 v140, s58, v187
	v_add_u32_e32 v172, s59, v187
	ds_read_b128 v[128:131], v140
	ds_read_b128 v[132:135], v140 offset:1024
	ds_read_b128 v[136:139], v140 offset:2048
	ds_read_b128 v[140:143], v140 offset:3072
	ds_read_b128 v[144:147], v172
	ds_read_b128 v[148:151], v172 offset:1024
	ds_read_b128 v[168:171], v172 offset:2048
	ds_read_b128 v[172:175], v172 offset:3072
	s_add_u32 s22, s40, 0xb0000
	s_addc_u32 s23, s41, 0
	s_mov_b32 m0, s45
	v_lshl_add_u64 v[226:227], s[22:23], 0, v[152:153]
	ds_read_b128 v[176:179], v191 offset:32768
	ds_read_b128 v[180:183], v191 offset:33792
	ds_read_b128 v[194:197], v191 offset:34816
	ds_read_b128 v[198:201], v191 offset:35840
	ds_read_b128 v[204:207], v191 offset:36864
	ds_read_b128 v[208:211], v191 offset:37888
	ds_read_b128 v[212:215], v191 offset:38912
	ds_read_b128 v[216:219], v191 offset:39936
	global_load_lds_dwordx4 v[226:227], off
	s_mov_b32 m0, s46
	v_lshl_add_u64 v[226:227], s[22:23], 0, v[156:157]
	global_load_lds_dwordx4 v[226:227], off
	s_waitcnt vmcnt(8) lgkmcnt(0)
	s_setprio 1
	s_barrier
	v_mfma_f32_16x16x32_bf16 v[124:127], v[128:131], v[176:179], v[124:127]
	v_mfma_f32_16x16x32_bf16 v[120:123], v[136:139], v[176:179], v[120:123]
	v_mfma_f32_16x16x32_bf16 v[108:111], v[128:131], v[194:197], v[108:111]
	v_mfma_f32_16x16x32_bf16 v[104:107], v[136:139], v[194:197], v[104:107]
	v_mfma_f32_16x16x32_bf16 v[92:95], v[128:131], v[204:207], v[92:95]
	v_mfma_f32_16x16x32_bf16 v[88:91], v[136:139], v[204:207], v[88:91]
	v_mfma_f32_16x16x32_bf16 v[76:79], v[128:131], v[212:215], v[76:79]
	v_mfma_f32_16x16x32_bf16 v[72:75], v[136:139], v[212:215], v[72:75]
	v_mfma_f32_16x16x32_bf16 v[124:127], v[132:135], v[180:183], v[124:127]
	v_mfma_f32_16x16x32_bf16 v[120:123], v[140:143], v[180:183], v[120:123]
	v_mfma_f32_16x16x32_bf16 v[108:111], v[132:135], v[198:201], v[108:111]
	v_mfma_f32_16x16x32_bf16 v[104:107], v[140:143], v[198:201], v[104:107]
	v_mfma_f32_16x16x32_bf16 v[92:95], v[132:135], v[208:211], v[92:95]
	v_mfma_f32_16x16x32_bf16 v[88:91], v[140:143], v[208:211], v[88:91]
	v_mfma_f32_16x16x32_bf16 v[76:79], v[132:135], v[216:219], v[76:79]
	v_mfma_f32_16x16x32_bf16 v[72:75], v[140:143], v[216:219], v[72:75]
	s_setprio 0
	s_setprio 1
	v_mfma_f32_16x16x32_bf16 v[116:119], v[144:147], v[176:179], v[116:119]
	v_mfma_f32_16x16x32_bf16 v[112:115], v[168:171], v[176:179], v[112:115]
	v_mfma_f32_16x16x32_bf16 v[100:103], v[144:147], v[194:197], v[100:103]
	v_mfma_f32_16x16x32_bf16 v[96:99], v[168:171], v[194:197], v[96:99]
	v_mfma_f32_16x16x32_bf16 v[84:87], v[144:147], v[204:207], v[84:87]
	v_mfma_f32_16x16x32_bf16 v[80:83], v[168:171], v[204:207], v[80:83]
	v_mfma_f32_16x16x32_bf16 v[68:71], v[144:147], v[212:215], v[68:71]
	v_mfma_f32_16x16x32_bf16 v[64:67], v[168:171], v[212:215], v[64:67]
	v_mfma_f32_16x16x32_bf16 v[116:119], v[148:151], v[180:183], v[116:119]
	v_mfma_f32_16x16x32_bf16 v[112:115], v[172:175], v[180:183], v[112:115]
	v_mfma_f32_16x16x32_bf16 v[100:103], v[148:151], v[198:201], v[100:103]
	v_mfma_f32_16x16x32_bf16 v[96:99], v[172:175], v[198:201], v[96:99]
	v_mfma_f32_16x16x32_bf16 v[84:87], v[148:151], v[208:211], v[84:87]
	v_mfma_f32_16x16x32_bf16 v[80:83], v[172:175], v[208:211], v[80:83]
	v_mfma_f32_16x16x32_bf16 v[68:71], v[148:151], v[216:219], v[68:71]
	v_mfma_f32_16x16x32_bf16 v[64:67], v[172:175], v[216:219], v[64:67]
	s_setprio 0
	s_barrier
	s_add_i32 s22, s58, s42
	v_lshl_add_u64 v[184:185], v[184:185], 0, s[30:31]
	s_mov_b32 m0, s22
	ds_read_b128 v[176:179], v191 offset:49152
	ds_read_b128 v[180:183], v191 offset:50176
	ds_read_b128 v[194:197], v191 offset:51200
	ds_read_b128 v[198:201], v191 offset:52224
	ds_read_b128 v[204:207], v191 offset:53248
	ds_read_b128 v[208:211], v191 offset:54272
	ds_read_b128 v[212:215], v191 offset:55296
	ds_read_b128 v[216:219], v191 offset:56320
	global_load_lds_dwordx4 v[184:185], off
	s_add_i32 m0, s22, 0x2000
	s_add_u32 s22, s38, 0xb0080
	v_lshl_add_u64 v[184:185], v[220:221], 0, s[30:31]
	s_addc_u32 s23, s39, 0
	s_add_i32 s38, s59, s42
	global_load_lds_dwordx4 v[184:185], off
	s_mov_b32 m0, s38
	v_lshl_add_u64 v[184:185], s[22:23], 0, v[154:155]
	global_load_lds_dwordx4 v[184:185], off
	s_add_i32 m0, s38, 0x2000
	v_lshl_add_u64 v[184:185], s[22:23], 0, v[158:159]
	global_load_lds_dwordx4 v[184:185], off
	s_mov_b32 m0, s33
	v_lshl_add_u64 v[184:185], v[222:223], 0, s[30:31]
	global_load_lds_dwordx4 v[184:185], off
	s_mov_b32 m0, s48
	v_lshl_add_u64 v[184:185], v[224:225], 0, s[30:31]
	global_load_lds_dwordx4 v[184:185], off
	s_waitcnt vmcnt(8) lgkmcnt(0)
	s_setprio 1
	s_barrier
	v_mfma_f32_16x16x32_bf16 v[60:63], v[128:131], v[176:179], v[60:63]
	v_mfma_f32_16x16x32_bf16 v[56:59], v[136:139], v[176:179], v[56:59]
	v_mfma_f32_16x16x32_bf16 v[44:47], v[128:131], v[194:197], v[44:47]
	v_mfma_f32_16x16x32_bf16 v[40:43], v[136:139], v[194:197], v[40:43]
	v_mfma_f32_16x16x32_bf16 v[28:31], v[128:131], v[204:207], v[28:31]
	v_mfma_f32_16x16x32_bf16 v[24:27], v[136:139], v[204:207], v[24:27]
	v_mfma_f32_16x16x32_bf16 v[12:15], v[128:131], v[212:215], v[12:15]
	v_mfma_f32_16x16x32_bf16 v[8:11], v[136:139], v[212:215], v[8:11]
	v_mfma_f32_16x16x32_bf16 v[60:63], v[132:135], v[180:183], v[60:63]
	v_mfma_f32_16x16x32_bf16 v[56:59], v[140:143], v[180:183], v[56:59]
	v_mfma_f32_16x16x32_bf16 v[44:47], v[132:135], v[198:201], v[44:47]
	v_mfma_f32_16x16x32_bf16 v[40:43], v[140:143], v[198:201], v[40:43]
	v_mfma_f32_16x16x32_bf16 v[28:31], v[132:135], v[208:211], v[28:31]
	v_mfma_f32_16x16x32_bf16 v[24:27], v[140:143], v[208:211], v[24:27]
	v_mfma_f32_16x16x32_bf16 v[12:15], v[132:135], v[216:219], v[12:15]
	v_mfma_f32_16x16x32_bf16 v[8:11], v[140:143], v[216:219], v[8:11]
	s_setprio 0
	s_setprio 1
	v_mfma_f32_16x16x32_bf16 v[52:55], v[144:147], v[176:179], v[52:55]
	v_mfma_f32_16x16x32_bf16 v[48:51], v[168:171], v[176:179], v[48:51]
	v_mfma_f32_16x16x32_bf16 v[36:39], v[144:147], v[194:197], v[36:39]
	v_mfma_f32_16x16x32_bf16 v[32:35], v[168:171], v[194:197], v[32:35]
	v_mfma_f32_16x16x32_bf16 v[20:23], v[144:147], v[204:207], v[20:23]
	v_mfma_f32_16x16x32_bf16 v[16:19], v[168:171], v[204:207], v[16:19]
	v_mfma_f32_16x16x32_bf16 v[4:7], v[144:147], v[212:215], v[4:7]
	v_mfma_f32_16x16x32_bf16 v[0:3], v[168:171], v[212:215], v[0:3]
	v_mfma_f32_16x16x32_bf16 v[52:55], v[148:151], v[180:183], v[52:55]
	v_mfma_f32_16x16x32_bf16 v[48:51], v[172:175], v[180:183], v[48:51]
	v_mfma_f32_16x16x32_bf16 v[36:39], v[148:151], v[198:201], v[36:39]
	v_mfma_f32_16x16x32_bf16 v[32:35], v[172:175], v[198:201], v[32:35]
	v_mfma_f32_16x16x32_bf16 v[20:23], v[148:151], v[208:211], v[20:23]
	v_mfma_f32_16x16x32_bf16 v[16:19], v[172:175], v[208:211], v[16:19]
	v_mfma_f32_16x16x32_bf16 v[4:7], v[148:151], v[216:219], v[4:7]
	v_mfma_f32_16x16x32_bf16 v[0:3], v[172:175], v[216:219], v[0:3]
	s_setprio 0
	s_add_i32 s57, s57, 2
	s_add_u32 s55, s55, 0x100
	s_addc_u32 s56, s56, 0
	s_cmp_gt_u32 s57, 41
	s_mov_b64 s[22:23], s[4:5]
	s_barrier
	s_cbranch_scc0 .LBB0_559
	s_and_b64 vcc, exec, s[34:35]
	s_cbranch_vccz .LBB0_562
	s_barrier

.LBB0_643:
	ds_read_b128 v[128:131], v191
	ds_read_b128 v[132:135], v191 offset:1024
	ds_read_b128 v[156:159], v191 offset:2048
	ds_read_b128 v[160:163], v191 offset:3072
	ds_read_b128 v[164:167], v192
	ds_read_b128 v[168:171], v192 offset:1024
	ds_read_b128 v[172:175], v192 offset:2048
	ds_read_b128 v[176:179], v192 offset:3072
	s_add_u32 s4, s22, 0xfffc0080
	s_addc_u32 s5, s23, -1
	s_cmp_eq_u32 s63, 12
	s_cselect_b32 s47, s13, s5
	s_cselect_b32 s46, s17, s4
	s_cselect_b32 s5, s33, s62
	s_cselect_b32 s4, s39, s41
	v_lshl_add_u64 v[224:225], s[22:23], 0, v[148:149]
	s_add_i32 m0, s49, 0xc000
	ds_read_b128 v[180:183], v193
	ds_read_b128 v[184:187], v193 offset:1024
	ds_read_b128 v[198:201], v193 offset:2048
	ds_read_b128 v[204:207], v193 offset:3072
	ds_read_b128 v[208:211], v193 offset:4096
	ds_read_b128 v[212:215], v193 offset:5120
	ds_read_b128 v[216:219], v193 offset:6144
	ds_read_b128 v[220:223], v193 offset:7168
	global_load_lds_dwordx4 v[224:225], off
	s_add_i32 m0, s49, 0xe000
	v_lshl_add_u64 v[224:225], s[22:23], 0, v[150:151]
	global_load_lds_dwordx4 v[224:225], off
	s_waitcnt vmcnt(8) lgkmcnt(0)
	s_setprio 1
	s_barrier
	v_mfma_f32_16x16x32_bf16 v[124:127], v[128:131], v[180:183], v[124:127]
	v_mfma_f32_16x16x32_bf16 v[120:123], v[156:159], v[180:183], v[120:123]
	v_mfma_f32_16x16x32_bf16 v[108:111], v[128:131], v[198:201], v[108:111]
	v_mfma_f32_16x16x32_bf16 v[104:107], v[156:159], v[198:201], v[104:107]
	v_mfma_f32_16x16x32_bf16 v[92:95], v[128:131], v[208:211], v[92:95]
	v_mfma_f32_16x16x32_bf16 v[88:91], v[156:159], v[208:211], v[88:91]
	v_mfma_f32_16x16x32_bf16 v[76:79], v[128:131], v[216:219], v[76:79]
	v_mfma_f32_16x16x32_bf16 v[72:75], v[156:159], v[216:219], v[72:75]
	v_mfma_f32_16x16x32_bf16 v[124:127], v[132:135], v[184:187], v[124:127]
	v_mfma_f32_16x16x32_bf16 v[120:123], v[160:163], v[184:187], v[120:123]
	v_mfma_f32_16x16x32_bf16 v[108:111], v[132:135], v[204:207], v[108:111]
	v_mfma_f32_16x16x32_bf16 v[104:107], v[160:163], v[204:207], v[104:107]
	v_mfma_f32_16x16x32_bf16 v[92:95], v[132:135], v[212:215], v[92:95]
	v_mfma_f32_16x16x32_bf16 v[88:91], v[160:163], v[212:215], v[88:91]
	v_mfma_f32_16x16x32_bf16 v[76:79], v[132:135], v[220:223], v[76:79]
	v_mfma_f32_16x16x32_bf16 v[72:75], v[160:163], v[220:223], v[72:75]
	s_setprio 0
	s_setprio 1
	v_mfma_f32_16x16x32_bf16 v[116:119], v[164:167], v[180:183], v[116:119]
	v_mfma_f32_16x16x32_bf16 v[112:115], v[172:175], v[180:183], v[112:115]
	v_mfma_f32_16x16x32_bf16 v[100:103], v[164:167], v[198:201], v[100:103]
	v_mfma_f32_16x16x32_bf16 v[96:99], v[172:175], v[198:201], v[96:99]
	v_mfma_f32_16x16x32_bf16 v[84:87], v[164:167], v[208:211], v[84:87]
	v_mfma_f32_16x16x32_bf16 v[80:83], v[172:175], v[208:211], v[80:83]
	v_mfma_f32_16x16x32_bf16 v[68:71], v[164:167], v[216:219], v[68:71]
	v_mfma_f32_16x16x32_bf16 v[64:67], v[172:175], v[216:219], v[64:67]
	v_mfma_f32_16x16x32_bf16 v[116:119], v[168:171], v[184:187], v[116:119]
	v_mfma_f32_16x16x32_bf16 v[112:115], v[176:179], v[184:187], v[112:115]
	v_mfma_f32_16x16x32_bf16 v[100:103], v[168:171], v[204:207], v[100:103]
	v_mfma_f32_16x16x32_bf16 v[96:99], v[176:179], v[204:207], v[96:99]
	v_mfma_f32_16x16x32_bf16 v[84:87], v[168:171], v[212:215], v[84:87]
	v_mfma_f32_16x16x32_bf16 v[80:83], v[176:179], v[212:215], v[80:83]
	v_mfma_f32_16x16x32_bf16 v[68:71], v[168:171], v[220:223], v[68:71]
	v_mfma_f32_16x16x32_bf16 v[64:67], v[176:179], v[220:223], v[64:67]
	s_setprio 0
	s_barrier
	s_add_i32 s64, s59, s48
	v_lshl_add_u64 v[224:225], s[4:5], 0, v[138:139]
	s_mov_b32 m0, s64
	ds_read_b128 v[180:183], v193 offset:16384
	ds_read_b128 v[184:187], v193 offset:17408
	ds_read_b128 v[198:201], v193 offset:18432
	ds_read_b128 v[204:207], v193 offset:19456
	ds_read_b128 v[208:211], v193 offset:20480
	ds_read_b128 v[212:215], v193 offset:21504
	ds_read_b128 v[216:219], v193 offset:22528
	ds_read_b128 v[220:223], v193 offset:23552
	global_load_lds_dwordx4 v[224:225], off
	s_add_i32 m0, s64, 0x2000
	s_add_u32 s64, s4, 0x40000
	v_lshl_add_u64 v[226:227], s[4:5], 0, v[142:143]
	s_addc_u32 s65, s5, 0
	s_add_i32 s66, s60, s48
	global_load_lds_dwordx4 v[226:227], off
	v_lshl_add_u64 v[228:229], s[64:65], 0, v[138:139]
	s_mov_b32 m0, s66
	v_lshl_add_u64 v[230:231], s[46:47], 0, v[140:141]
	global_load_lds_dwordx4 v[228:229], off
	s_add_i32 m0, s66, 0x2000
	v_lshl_add_u64 v[228:229], s[64:65], 0, v[142:143]
	global_load_lds_dwordx4 v[228:229], off
	s_mov_b32 m0, s49
	v_lshl_add_u64 v[228:229], s[46:47], 0, v[136:137]
	global_load_lds_dwordx4 v[228:229], off
	s_mov_b32 m0, s50
	s_nop 0
	global_load_lds_dwordx4 v[230:231], off
	s_waitcnt vmcnt(8) lgkmcnt(0)
	s_setprio 1
	s_barrier
	v_mfma_f32_16x16x32_bf16 v[60:63], v[128:131], v[180:183], v[60:63]
	v_mfma_f32_16x16x32_bf16 v[56:59], v[156:159], v[180:183], v[56:59]
	v_mfma_f32_16x16x32_bf16 v[44:47], v[128:131], v[198:201], v[44:47]
	v_mfma_f32_16x16x32_bf16 v[40:43], v[156:159], v[198:201], v[40:43]
	v_mfma_f32_16x16x32_bf16 v[28:31], v[128:131], v[208:211], v[28:31]
	v_mfma_f32_16x16x32_bf16 v[24:27], v[156:159], v[208:211], v[24:27]
	v_mfma_f32_16x16x32_bf16 v[12:15], v[128:131], v[216:219], v[12:15]
	v_mfma_f32_16x16x32_bf16 v[8:11], v[156:159], v[216:219], v[8:11]
	v_mfma_f32_16x16x32_bf16 v[60:63], v[132:135], v[184:187], v[60:63]
	v_mfma_f32_16x16x32_bf16 v[56:59], v[160:163], v[184:187], v[56:59]
	v_mfma_f32_16x16x32_bf16 v[44:47], v[132:135], v[204:207], v[44:47]
	v_mfma_f32_16x16x32_bf16 v[40:43], v[160:163], v[204:207], v[40:43]
	v_mfma_f32_16x16x32_bf16 v[28:31], v[132:135], v[212:215], v[28:31]
	v_mfma_f32_16x16x32_bf16 v[24:27], v[160:163], v[212:215], v[24:27]
	v_mfma_f32_16x16x32_bf16 v[12:15], v[132:135], v[220:223], v[12:15]
	v_mfma_f32_16x16x32_bf16 v[8:11], v[160:163], v[220:223], v[8:11]
	s_setprio 0
	s_setprio 1
	v_mfma_f32_16x16x32_bf16 v[52:55], v[164:167], v[180:183], v[52:55]
	v_mfma_f32_16x16x32_bf16 v[48:51], v[172:175], v[180:183], v[48:51]
	v_mfma_f32_16x16x32_bf16 v[36:39], v[164:167], v[198:201], v[36:39]
	v_mfma_f32_16x16x32_bf16 v[32:35], v[172:175], v[198:201], v[32:35]
	v_mfma_f32_16x16x32_bf16 v[20:23], v[164:167], v[208:211], v[20:23]
	v_mfma_f32_16x16x32_bf16 v[16:19], v[172:175], v[208:211], v[16:19]
	v_mfma_f32_16x16x32_bf16 v[4:7], v[164:167], v[216:219], v[4:7]
	v_mfma_f32_16x16x32_bf16 v[0:3], v[172:175], v[216:219], v[0:3]
	v_mfma_f32_16x16x32_bf16 v[52:55], v[168:171], v[184:187], v[52:55]
	v_mfma_f32_16x16x32_bf16 v[48:51], v[176:179], v[184:187], v[48:51]
	v_mfma_f32_16x16x32_bf16 v[36:39], v[168:171], v[204:207], v[36:39]
	v_mfma_f32_16x16x32_bf16 v[32:35], v[176:179], v[204:207], v[32:35]
	v_mfma_f32_16x16x32_bf16 v[20:23], v[168:171], v[212:215], v[20:23]
	v_mfma_f32_16x16x32_bf16 v[16:19], v[176:179], v[212:215], v[16:19]
	v_mfma_f32_16x16x32_bf16 v[4:7], v[168:171], v[220:223], v[4:7]
	v_mfma_f32_16x16x32_bf16 v[0:3], v[176:179], v[220:223], v[0:3]
	s_setprio 0
	s_barrier
	s_add_i32 s64, 0, 0x18000
	v_add_u32_e32 v144, s64, v189
	s_add_i32 s65, 0, 0x1c000
	ds_read_b128 v[128:131], v144
	ds_read_b128 v[132:135], v144 offset:1024
	ds_read_b128 v[156:159], v144 offset:2048
	ds_read_b128 v[160:163], v144 offset:3072
	v_add_u32_e32 v144, s65, v189
	ds_read_b128 v[164:167], v144
	ds_read_b128 v[168:171], v144 offset:1024
	ds_read_b128 v[172:175], v144 offset:2048
	ds_read_b128 v[176:179], v144 offset:3072
	s_add_u32 s46, s46, 0x40000
	s_addc_u32 s47, s47, 0
	s_mov_b32 m0, s51
	v_lshl_add_u64 v[232:233], s[46:47], 0, v[136:137]
	ds_read_b128 v[180:183], v193 offset:32768
	ds_read_b128 v[184:187], v193 offset:33792
	ds_read_b128 v[198:201], v193 offset:34816
	ds_read_b128 v[204:207], v193 offset:35840
	ds_read_b128 v[208:211], v193 offset:36864
	ds_read_b128 v[212:215], v193 offset:37888
	ds_read_b128 v[216:219], v193 offset:38912
	ds_read_b128 v[220:223], v193 offset:39936
	global_load_lds_dwordx4 v[232:233], off
	s_mov_b32 m0, s52
	v_lshl_add_u64 v[232:233], s[46:47], 0, v[140:141]
	global_load_lds_dwordx4 v[232:233], off
	s_waitcnt vmcnt(8) lgkmcnt(0)
	s_setprio 1
	s_barrier
	v_mfma_f32_16x16x32_bf16 v[124:127], v[128:131], v[180:183], v[124:127]
	v_mfma_f32_16x16x32_bf16 v[120:123], v[156:159], v[180:183], v[120:123]
	v_mfma_f32_16x16x32_bf16 v[108:111], v[128:131], v[198:201], v[108:111]
	v_mfma_f32_16x16x32_bf16 v[104:107], v[156:159], v[198:201], v[104:107]
	v_mfma_f32_16x16x32_bf16 v[92:95], v[128:131], v[208:211], v[92:95]
	v_mfma_f32_16x16x32_bf16 v[88:91], v[156:159], v[208:211], v[88:91]
	v_mfma_f32_16x16x32_bf16 v[76:79], v[128:131], v[216:219], v[76:79]
	v_mfma_f32_16x16x32_bf16 v[72:75], v[156:159], v[216:219], v[72:75]
	v_mfma_f32_16x16x32_bf16 v[124:127], v[132:135], v[184:187], v[124:127]
	v_mfma_f32_16x16x32_bf16 v[120:123], v[160:163], v[184:187], v[120:123]
	v_mfma_f32_16x16x32_bf16 v[108:111], v[132:135], v[204:207], v[108:111]
	v_mfma_f32_16x16x32_bf16 v[104:107], v[160:163], v[204:207], v[104:107]
	v_mfma_f32_16x16x32_bf16 v[92:95], v[132:135], v[212:215], v[92:95]
	v_mfma_f32_16x16x32_bf16 v[88:91], v[160:163], v[212:215], v[88:91]
	v_mfma_f32_16x16x32_bf16 v[76:79], v[132:135], v[220:223], v[76:79]
	v_mfma_f32_16x16x32_bf16 v[72:75], v[160:163], v[220:223], v[72:75]
	s_setprio 0
	s_setprio 1
	v_mfma_f32_16x16x32_bf16 v[116:119], v[164:167], v[180:183], v[116:119]
	v_mfma_f32_16x16x32_bf16 v[112:115], v[172:175], v[180:183], v[112:115]
	v_mfma_f32_16x16x32_bf16 v[100:103], v[164:167], v[198:201], v[100:103]
	v_mfma_f32_16x16x32_bf16 v[96:99], v[172:175], v[198:201], v[96:99]
	v_mfma_f32_16x16x32_bf16 v[84:87], v[164:167], v[208:211], v[84:87]
	v_mfma_f32_16x16x32_bf16 v[80:83], v[172:175], v[208:211], v[80:83]
	v_mfma_f32_16x16x32_bf16 v[68:71], v[164:167], v[216:219], v[68:71]
	v_mfma_f32_16x16x32_bf16 v[64:67], v[172:175], v[216:219], v[64:67]
	v_mfma_f32_16x16x32_bf16 v[116:119], v[168:171], v[184:187], v[116:119]
	v_mfma_f32_16x16x32_bf16 v[112:115], v[176:179], v[184:187], v[112:115]
	v_mfma_f32_16x16x32_bf16 v[100:103], v[168:171], v[204:207], v[100:103]
	v_mfma_f32_16x16x32_bf16 v[96:99], v[176:179], v[204:207], v[96:99]
	v_mfma_f32_16x16x32_bf16 v[84:87], v[168:171], v[212:215], v[84:87]
	v_mfma_f32_16x16x32_bf16 v[80:83], v[176:179], v[212:215], v[80:83]
	v_mfma_f32_16x16x32_bf16 v[68:71], v[168:171], v[220:223], v[68:71]
	v_mfma_f32_16x16x32_bf16 v[64:67], v[176:179], v[220:223], v[64:67]
	s_setprio 0
	s_barrier
	s_add_i32 s46, s64, s48
	v_lshl_add_u64 v[224:225], v[224:225], 0, s[30:31]
	s_mov_b32 m0, s46
	ds_read_b128 v[180:183], v193 offset:49152
	ds_read_b128 v[184:187], v193 offset:50176
	ds_read_b128 v[198:201], v193 offset:51200
	ds_read_b128 v[204:207], v193 offset:52224
	ds_read_b128 v[208:211], v193 offset:53248
	ds_read_b128 v[212:215], v193 offset:54272
	ds_read_b128 v[216:219], v193 offset:55296
	ds_read_b128 v[220:223], v193 offset:56320
	global_load_lds_dwordx4 v[224:225], off
	s_add_i32 m0, s46, 0x2000
	s_add_u32 s4, s4, 0x40080
	v_lshl_add_u64 v[224:225], v[226:227], 0, s[30:31]
	s_addc_u32 s5, s5, 0
	s_add_i32 s46, s65, s48
	global_load_lds_dwordx4 v[224:225], off
	s_mov_b32 m0, s46
	v_lshl_add_u64 v[224:225], s[4:5], 0, v[138:139]
	global_load_lds_dwordx4 v[224:225], off
	s_add_i32 m0, s46, 0x2000
	v_lshl_add_u64 v[224:225], s[4:5], 0, v[142:143]
	global_load_lds_dwordx4 v[224:225], off
	s_mov_b32 m0, s56
	v_lshl_add_u64 v[224:225], v[228:229], 0, s[30:31]
	global_load_lds_dwordx4 v[224:225], off
	s_mov_b32 m0, s57
	v_lshl_add_u64 v[224:225], v[230:231], 0, s[30:31]
	global_load_lds_dwordx4 v[224:225], off
	s_waitcnt vmcnt(8) lgkmcnt(0)
	s_setprio 1
	s_barrier
	v_mfma_f32_16x16x32_bf16 v[60:63], v[128:131], v[180:183], v[60:63]
	v_mfma_f32_16x16x32_bf16 v[56:59], v[156:159], v[180:183], v[56:59]
	v_mfma_f32_16x16x32_bf16 v[44:47], v[128:131], v[198:201], v[44:47]
	v_mfma_f32_16x16x32_bf16 v[40:43], v[156:159], v[198:201], v[40:43]
	v_mfma_f32_16x16x32_bf16 v[28:31], v[128:131], v[208:211], v[28:31]
	v_mfma_f32_16x16x32_bf16 v[24:27], v[156:159], v[208:211], v[24:27]
	v_mfma_f32_16x16x32_bf16 v[12:15], v[128:131], v[216:219], v[12:15]
	v_mfma_f32_16x16x32_bf16 v[8:11], v[156:159], v[216:219], v[8:11]
	v_mfma_f32_16x16x32_bf16 v[60:63], v[132:135], v[184:187], v[60:63]
	v_mfma_f32_16x16x32_bf16 v[56:59], v[160:163], v[184:187], v[56:59]
	v_mfma_f32_16x16x32_bf16 v[44:47], v[132:135], v[204:207], v[44:47]
	v_mfma_f32_16x16x32_bf16 v[40:43], v[160:163], v[204:207], v[40:43]
	v_mfma_f32_16x16x32_bf16 v[28:31], v[132:135], v[212:215], v[28:31]
	v_mfma_f32_16x16x32_bf16 v[24:27], v[160:163], v[212:215], v[24:27]
	v_mfma_f32_16x16x32_bf16 v[12:15], v[132:135], v[220:223], v[12:15]
	v_mfma_f32_16x16x32_bf16 v[8:11], v[160:163], v[220:223], v[8:11]
	s_setprio 0
	s_setprio 1
	v_mfma_f32_16x16x32_bf16 v[52:55], v[164:167], v[180:183], v[52:55]
	v_mfma_f32_16x16x32_bf16 v[48:51], v[172:175], v[180:183], v[48:51]
	v_mfma_f32_16x16x32_bf16 v[36:39], v[164:167], v[198:201], v[36:39]
	v_mfma_f32_16x16x32_bf16 v[32:35], v[172:175], v[198:201], v[32:35]
	v_mfma_f32_16x16x32_bf16 v[20:23], v[164:167], v[208:211], v[20:23]
	v_mfma_f32_16x16x32_bf16 v[16:19], v[172:175], v[208:211], v[16:19]
	v_mfma_f32_16x16x32_bf16 v[4:7], v[164:167], v[216:219], v[4:7]
	v_mfma_f32_16x16x32_bf16 v[0:3], v[172:175], v[216:219], v[0:3]
	v_mfma_f32_16x16x32_bf16 v[52:55], v[168:171], v[184:187], v[52:55]
	v_mfma_f32_16x16x32_bf16 v[48:51], v[176:179], v[184:187], v[48:51]
	v_mfma_f32_16x16x32_bf16 v[36:39], v[168:171], v[204:207], v[36:39]
	v_mfma_f32_16x16x32_bf16 v[32:35], v[176:179], v[204:207], v[32:35]
	v_mfma_f32_16x16x32_bf16 v[20:23], v[168:171], v[212:215], v[20:23]
	v_mfma_f32_16x16x32_bf16 v[16:19], v[176:179], v[212:215], v[16:19]
	v_mfma_f32_16x16x32_bf16 v[4:7], v[168:171], v[220:223], v[4:7]
	v_mfma_f32_16x16x32_bf16 v[0:3], v[176:179], v[220:223], v[0:3]
	s_setprio 0
	s_add_i32 s63, s63, 2
	s_add_u32 s22, s22, 0x100
	s_addc_u32 s23, s23, 0
	s_add_u32 s41, s41, 0x100
	s_addc_u32 s62, s62, 0
	s_cmp_gt_u32 s63, 13
	s_barrier
	s_cbranch_scc0 .LBB0_643
	s_and_b64 vcc, exec, s[34:35]
	s_cbranch_vccz .LBB0_646
	s_barrier

.LBB0_764:
	s_mov_b64 s[8:9], s[0:1]
	v_mov_b32_e32 v36, v202
	s_load_dwordx2 s[92:93], s[8:9], 0xa0
	s_ashr_i32 s63, s62, 31
	v_readfirstlane_b32 s14, v36
	s_lshl_b32 s20, s60, 8
	s_lshl_b32 s6, s35, 7
	s_ashr_i32 s12, s14, 6
	s_lshl_b64 s[86:87], s[62:63], 13
	s_ashr_i32 s7, s20, 31
	s_add_u32 s10, s86, s20
	s_addc_u32 s37, s87, s7
	s_lshl_b32 s13, s12, 5
	s_ashr_i32 s24, s13, 31
	s_add_u32 s8, s10, s13
	s_addc_u32 s9, s37, s24
	s_ashr_i32 s7, s6, 31
	s_lshl_b64 s[80:81], s[8:9], 10
	s_lshl_b64 s[74:75], s[62:63], 24
	s_lshl_b64 s[64:65], s[6:7], 1
	s_waitcnt lgkmcnt(0)
	s_add_u32 s6, s92, s74
	s_addc_u32 s7, s93, s75
	v_and_b32_e32 v207, 63, v36
	s_add_u32 s6, s6, s64
	s_addc_u32 s7, s7, s65
	v_lshlrev_b32_e32 v2, 11, v207
	v_mov_b32_e32 v3, v146
	s_lshl_b32 s88, s12, 3
	v_lshl_add_u64 v[2:3], s[6:7], 0, v[2:3]
	s_ashr_i32 s89, s88, 31
	s_lshl_b32 s8, s12, 4
	v_bfe_u32 v37, v36, 2, 4
	v_lshl_add_u64 v[2:3], s[88:89], 1, v[2:3]
	v_and_or_b32 v211, s8, 48, v37
	v_lshl_add_u64 v[188:189], v[2:3], 0, s[16:17]
	v_lshlrev_b32_e32 v2, 11, v211
	v_mov_b32_e32 v3, v146
	v_lshl_add_u64 v[2:3], s[6:7], 0, v[2:3]
	s_ashr_i32 s6, s14, 3
	s_and_b32 s90, s6, 0xffffffe0
	s_ashr_i32 s91, s90, 31
	v_lshlrev_b32_e32 v210, 3, v36
	s_lshl_b32 s25, s12, 10
	v_and_b32_e32 v38, 24, v210
	s_cmp_lg_u32 0, -1
	v_and_b32_e32 v208, 31, v36
	v_lshl_add_u64 v[2:3], s[90:91], 1, v[2:3]
	v_lshlrev_b32_e32 v186, 1, v38
	v_mov_b32_e32 v187, v146
	s_cselect_b32 s6, 0, 0
	v_bfe_u32 v209, v36, 5, 1
	v_lshl_add_u64 v[2:3], v[2:3], 0, v[186:187]
	s_add_i32 s56, s25, s6
	v_lshlrev_b32_e32 v1, 11, v208
	v_lshl_add_u64 v[34:35], v[2:3], 0, s[58:59]
	s_add_i32 s55, s56, 0x6000
	s_add_i32 s54, s56, 0xe000
	s_andn2_b64 vcc, exec, s[4:5]
	v_lshl_or_b32 v184, v209, 4, v1
	s_cbranch_vccnz .LBB0_766
	s_lshl_b64 s[6:7], s[80:81], 1
	s_add_u32 s6, s92, s6
	s_addc_u32 s7, s93, s7
	s_add_u32 s6, s6, s64
	s_addc_u32 s7, s7, s65
	v_mov_b32_e32 v185, v146
	v_lshl_add_u64 v[2:3], s[6:7], 0, v[184:185]
	v_lshl_add_u64 v[4:5], v[2:3], 0, s[30:31]
	v_add_co_u32_e32 v2, vcc, s97, v2
	s_cmp_lg_u32 0, -1
	s_nop 0
	v_addc_co_u32_e32 v3, vcc, 0, v3, vcc
	global_load_dwordx4 v[152:155], v[4:5], off offset:32
	global_load_dwordx4 v[156:159], v[4:5], off offset:64
	global_load_dwordx4 v[148:151], v[2:3], off
	global_load_dwordx4 v[160:163], v[4:5], off offset:96
	s_mov_b32 m0, s56
	s_nop 0
	global_load_lds_dwordx4 v[188:189], off
	s_mov_b64 s[22:23], 0x20000
	s_mov_b32 m0, s55
	s_nop 0
	global_load_lds_dwordx4 v[34:35], off
	s_mov_b64 s[6:7], 0x80
	s_mov_b32 m0, s54
	v_lshl_add_u64 v[2:3], v[34:35], 0, s[6:7]
	global_load_lds_dwordx4 v[2:3], off
	s_cselect_b32 s6, 0, 0
	s_add_i32 s8, s6, s25
	v_lshl_add_u64 v[2:3], v[188:189], 0, s[22:23]
	s_add_i32 s6, s8, 0x2000
	s_mov_b32 m0, s6
	s_nop 0
	global_load_lds_dwordx4 v[2:3], off
	v_lshl_add_u64 v[2:3], v[34:35], 0, s[22:23]
	s_add_i32 s6, s8, 0x8000
	s_mov_b32 m0, s6
	s_nop 0
	global_load_lds_dwordx4 v[2:3], off
	s_mov_b64 s[6:7], 0x20080
	v_lshl_add_u64 v[2:3], v[34:35], 0, s[6:7]
	s_add_i32 s6, s8, 0x10000
	s_mov_b32 m0, s6
	s_nop 0
	global_load_lds_dwordx4 v[2:3], off
	s_mov_b64 s[6:7], 0x40000
	v_lshl_add_u64 v[2:3], v[188:189], 0, s[6:7]
	s_addk_i32 s8, 0x4000
	s_mov_b32 m0, s8
	s_nop 0
	global_load_lds_dwordx4 v[2:3], off

.LBB0_823:
	s_mov_b64 s[6:7], 0x60000
	s_mov_b32 m0, s56
	v_lshl_add_u64 v[44:45], v[188:189], 0, s[6:7]
	global_load_lds_dwordx4 v[44:45], off
	v_cndmask_b32_e64 v43, 0, 1, s[4:5]
	v_cmp_ne_u32_e64 s[6:7], 1, v43
	s_andn2_b64 vcc, exec, s[4:5]
	s_cbranch_vccz .LBB0_776
	s_branch .LBB0_777

.LBB0_826:
	s_mov_b64 s[22:23], s[0:1]
	s_waitcnt vmcnt(0) lgkmcnt(0)
	s_barrier
	s_load_dwordx2 s[22:23], s[22:23], 0xa0
	s_lshl_b64 s[4:5], s[62:63], 23
	s_lshl_b64 s[92:93], s[4:5], 1
	v_lshlrev_b32_e32 v83, 10, v207
	v_lshlrev_b32_e32 v82, 10, v211
	s_waitcnt lgkmcnt(0)
	s_add_u32 s4, s22, s92
	s_addc_u32 s5, s23, s93
	s_add_u32 s4, s4, s64
	v_lshlrev_b32_e32 v84, 1, v83
	v_mov_b32_e32 v85, v146
	s_addc_u32 s5, s5, s65
	v_lshlrev_b32_e32 v82, 1, v82
	v_mov_b32_e32 v83, v146
	s_ashr_i32 s61, s60, 31
	v_lshl_add_u64 v[84:85], s[4:5], 0, v[84:85]
	v_lshl_add_u64 v[82:83], s[4:5], 0, v[82:83]
	s_lshl_b64 s[4:5], s[60:61], 8
	s_add_u32 s61, s4, s86
	s_addc_u32 s63, s5, s87
	s_add_u32 s4, s61, s13
	s_addc_u32 s5, s63, s24
	s_lshl_b64 s[4:5], s[4:5], 11
	s_add_u32 s4, s22, s4
	v_lshl_add_u64 v[84:85], s[88:89], 1, v[84:85]
	s_mov_b64 s[28:29], 0x8800080
	v_lshl_add_u64 v[82:83], s[90:91], 1, v[82:83]
	v_mov_b32_e32 v187, v146
	s_addc_u32 s5, s23, s5
	v_lshl_add_u64 v[86:87], v[84:85], 0, s[28:29]
	v_lshl_add_u64 v[82:83], v[82:83], 0, v[186:187]
	s_add_u32 s4, s4, s64
	s_mov_b32 m0, s56
	s_nop 0
	global_load_lds_dwordx4 v[86:87], off
	v_lshl_add_u64 v[88:89], v[82:83], 0, s[58:59]
	s_addc_u32 s5, s5, s65
	s_mov_b32 m0, s55
	s_nop 0
	global_load_lds_dwordx4 v[88:89], off
	s_mov_b64 s[22:23], 0xc800080
	s_mov_b32 m0, s54
	v_lshl_add_u64 v[86:87], v[82:83], 0, s[22:23]
	global_load_lds_dwordx4 v[86:87], off
	s_cmp_lg_u32 0, -1
	s_mov_b64 s[22:23], 0x8820080
	s_cselect_b32 s9, 0, 0
	v_lshl_add_u64 v[86:87], v[84:85], 0, s[22:23]
	s_add_i32 s9, s9, s25
	s_mov_b64 s[22:23], 0xc820000
	s_add_i32 s13, s9, 0x2000
	s_mov_b32 m0, s13
	s_nop 0
	global_load_lds_dwordx4 v[86:87], off
	v_lshl_add_u64 v[86:87], v[82:83], 0, s[22:23]
	s_mov_b64 s[22:23], 0xc820080
	s_add_i32 s13, s9, 0x8000
	s_mov_b32 m0, s13
	s_nop 0
	global_load_lds_dwordx4 v[86:87], off
	v_lshl_add_u64 v[82:83], v[82:83], 0, s[22:23]
	s_mov_b64 s[22:23], 0x8840080
	s_add_i32 s13, s9, 0x10000
	s_mov_b32 m0, s13
	s_nop 0
	global_load_lds_dwordx4 v[82:83], off
	v_lshl_add_u64 v[82:83], v[84:85], 0, s[22:23]
	v_mov_b32_e32 v185, v146
	s_addk_i32 s9, 0x4000
	s_mov_b32 m0, s9
	s_nop 0
	global_load_lds_dwordx4 v[82:83], off
	v_lshl_add_u64 v[82:83], s[4:5], 0, v[184:185]
	v_lshl_add_u64 v[82:83], v[82:83], 0, s[30:31]
	global_load_dwordx4 v[148:151], v[82:83], off offset:128
	global_load_dwordx4 v[152:155], v[82:83], off offset:160
	global_load_dwordx4 v[156:159], v[82:83], off offset:192
	global_load_dwordx4 v[160:163], v[82:83], off offset:224
	v_add_u32_e32 v122, s8, v147
	ds_read_b64_tr_b16 v[82:83], v122 offset:24576
	ds_read_b64_tr_b16 v[84:85], v122 offset:25088
	ds_read_b64_tr_b16 v[86:87], v122 offset:28672
	ds_read_b64_tr_b16 v[88:89], v122 offset:29184
	s_waitcnt lgkmcnt(2)
	v_mfma_f32_32x32x16_bf16 v[18:33], v[164:167], v[82:85], v[18:33]
	ds_read_b64_tr_b16 v[90:91], v122 offset:57344
	ds_read_b64_tr_b16 v[92:93], v122 offset:57856
	s_waitcnt lgkmcnt(2)
	v_mfma_f32_32x32x16_bf16 v[50:65], v[164:167], v[86:89], v[50:65]
	ds_read_b64_tr_b16 v[82:83], v122 offset:61440
	ds_read_b64_tr_b16 v[84:85], v122 offset:61952
	s_waitcnt lgkmcnt(2)
	v_mfma_f32_32x32x16_bf16 v[34:49], v[164:167], v[90:93], v[34:49]
	ds_read_b64_tr_b16 v[118:119], v122 offset:25600
	ds_read_b64_tr_b16 v[120:121], v122 offset:26112
	s_waitcnt lgkmcnt(2)
	v_mfma_f32_32x32x16_bf16 v[2:17], v[164:167], v[82:85], v[2:17]
	ds_read_b64_tr_b16 v[114:115], v122 offset:29696
	ds_read_b64_tr_b16 v[116:117], v122 offset:30208
	v_max_f32_e32 v82, v98, v99
	v_max3_f32 v83, v100, v101, v67
	v_max3_f32 v82, v82, v66, v68
	v_max3_f32 v82, v82, v69, v102
	v_max3_f32 v83, v83, v104, v105
	v_max3_f32 v82, v82, v103, v70
	v_max3_f32 v83, v83, v72, v73
	v_max3_f32 v82, v82, v71, v106
	v_max3_f32 v83, v83, v108, v109
	v_max3_f32 v82, v82, v107, v74
	v_max3_f32 v83, v83, v76, v77
	v_max3_f32 v82, v82, v75, v110
	v_max3_f32 v83, v83, v112, v113
	v_max3_f32 v82, v82, v111, v78
	v_max3_f32 v83, v83, v80, v81
	v_max3_f32 v82, v82, v79, v83
	v_mov_b32_e32 v83, v82
	s_nop 1
	v_permlane32_swap_b32_e32 v82, v83
	v_max_f32_e32 v82, v82, v83
	v_cmp_lt_f32_e32 vcc, s15, v82
	s_cmp_lg_u64 vcc, 0
	s_cselect_b64 s[8:9], -1, 0
	s_cbranch_vccz .LBB0_830
	v_max_f32_e32 v82, v82, v82
	v_max_f32_e32 v123, 0, v82
	v_add_f32_e32 v82, v212, v123
	v_xor_b32_e32 v82, 0x80000000, v82
	v_mov_b32_e32 v83, v82
	v_mov_b32_e32 v84, v82
	v_mov_b32_e32 v85, v82
	v_mov_b32_e32 v86, v82
	v_mov_b32_e32 v87, v82
	v_mov_b32_e32 v88, v82
	v_mov_b32_e32 v89, v82
	v_mov_b32_e32 v90, v82
	v_mov_b32_e32 v91, v82
	v_mov_b32_e32 v92, v82
	v_mov_b32_e32 v93, v82
	v_mov_b32_e32 v94, v82
	v_mov_b32_e32 v95, v82
	v_mov_b32_e32 v96, v82
	v_mov_b32_e32 v97, v82
	v_cmp_gt_u32_e32 vcc, 32, v207
	v_exp_f32_e64 v82, -v123
	s_and_saveexec_b64 s[4:5], vcc
	s_mov_b64 s[86:87], 0x14800000
	ds_write_b32 v1, v82
	s_or_b64 exec, exec, s[4:5]
	v_sub_f32_e32 v113, v113, v123
	v_sub_f32_e32 v112, v112, v123
	v_sub_f32_e32 v111, v111, v123
	v_sub_f32_e32 v110, v110, v123
	v_sub_f32_e32 v109, v109, v123
	v_sub_f32_e32 v108, v108, v123
	v_sub_f32_e32 v107, v107, v123
	v_sub_f32_e32 v106, v106, v123
	v_sub_f32_e32 v105, v105, v123
	v_sub_f32_e32 v104, v104, v123
	v_sub_f32_e32 v103, v103, v123
	v_sub_f32_e32 v102, v102, v123
	v_sub_f32_e32 v101, v101, v123
	v_sub_f32_e32 v100, v100, v123
	v_sub_f32_e32 v99, v99, v123
	v_sub_f32_e32 v98, v98, v123
	v_sub_f32_e32 v81, v81, v123
	v_sub_f32_e32 v80, v80, v123
	v_sub_f32_e32 v79, v79, v123
	v_sub_f32_e32 v78, v78, v123
	v_sub_f32_e32 v77, v77, v123
	v_sub_f32_e32 v76, v76, v123
	v_sub_f32_e32 v75, v75, v123
	v_sub_f32_e32 v74, v74, v123
	v_sub_f32_e32 v73, v73, v123
	v_sub_f32_e32 v72, v72, v123
	v_sub_f32_e32 v71, v71, v123
	v_sub_f32_e32 v70, v70, v123
	v_sub_f32_e32 v69, v69, v123
	v_sub_f32_e32 v68, v68, v123
	v_sub_f32_e32 v67, v67, v123
	v_sub_f32_e32 v66, v66, v123
	v_mul_f32_e32 v213, v213, v82
	s_branch .LBB0_831

.LBB0_841:
	s_add_u32 s4, s22, s92
	s_addc_u32 s5, s23, s93
	s_add_u32 s4, s4, s64
	v_and_b32_e32 v1, 63, v34
	s_addc_u32 s5, s5, s65
	s_lshl_b32 s8, s12, 3
	v_lshlrev_b32_e32 v42, 11, v1
	v_mov_b32_e32 v43, v146
	s_ashr_i32 s9, s8, 31
	s_lshl_b32 s24, s12, 10
	v_lshl_add_u64 v[42:43], s[4:5], 0, v[42:43]
	s_cmp_lg_u32 0, -1
	v_lshl_add_u64 v[42:43], s[8:9], 1, v[42:43]
	s_cselect_b32 s4, 0, 0
	v_lshl_add_u64 v[188:189], v[42:43], 0, s[28:29]
	s_andn2_b64 vcc, exec, s[78:79]
	s_add_i32 s25, s24, s4
	s_cbranch_vccnz .LBB0_843
	s_mov_b64 s[4:5], 0x60000
	s_mov_b32 m0, s25
	v_lshl_add_u64 v[42:43], v[188:189], 0, s[4:5]
	global_load_lds_dwordx4 v[42:43], off

.LBB0_891:
	s_mov_b64 s[6:7], s[0:1]
	s_waitcnt vmcnt(0) lgkmcnt(0)
	s_barrier
	s_load_dwordx2 s[6:7], s[6:7], 0xa0
	s_ashr_i32 s14, s13, 31
	s_add_u32 s22, s61, s13
	s_addc_u32 s23, s63, s14
	s_lshl_b64 s[22:23], s[22:23], 11
	s_waitcnt lgkmcnt(0)
	s_add_u32 s5, s6, s22
	s_addc_u32 s7, s7, s23
	s_add_u32 s6, s5, s64
	v_and_b32_e32 v83, 56, v211
	s_addc_u32 s7, s7, s65
	v_lshlrev_b32_e32 v188, 1, v83
	v_mov_b32_e32 v189, v146
	v_lshl_add_u64 v[84:85], s[6:7], 0, v[188:189]
	v_lshlrev_b32_e32 v83, 8, v1
	v_lshl_add_u64 v[86:87], v[84:85], 0, s[86:87]
	v_and_b32_e32 v88, 0x3800, v83
	v_mov_b32_e32 v89, v146
	v_lshl_add_u64 v[90:91], v[86:87], 0, v[88:89]
	v_or_b32_e32 v92, 0x4000, v88
	v_mov_b32_e32 v93, v146
	v_or_b32_e32 v96, 0x8000, v88
	v_mov_b32_e32 v97, v146
	v_or_b32_e32 v88, 0xc000, v88
	s_mov_b64 s[6:7], 0x14800080
	v_lshl_add_u64 v[94:95], v[86:87], 0, v[92:93]
	v_lshl_add_u64 v[114:115], v[86:87], 0, v[96:97]
	v_lshl_add_u64 v[86:87], v[86:87], 0, v[88:89]
	v_lshl_add_u64 v[84:85], v[84:85], 0, s[6:7]
	global_load_dwordx4 v[130:133], v[94:95], off
	global_load_dwordx4 v[134:137], v[114:115], off
	global_load_dwordx4 v[138:141], v[90:91], off
	s_nop 0
	global_load_dwordx4 v[114:117], v[90:91], off offset:128
	v_lshl_add_u64 v[90:91], v[84:85], 0, v[92:93]
	global_load_dwordx4 v[142:145], v[86:87], off
	global_load_dwordx4 v[118:121], v[90:91], off
	v_lshl_add_u64 v[86:87], v[84:85], 0, v[96:97]
	v_lshl_add_u64 v[84:85], v[84:85], 0, v[88:89]
	global_load_dwordx4 v[122:125], v[86:87], off
	global_load_dwordx4 v[126:129], v[84:85], off
	v_lshlrev_b32_e32 v82, 10, v1
	s_andn2_b64 vcc, exec, s[66:67]
	s_cbranch_vccnz .LBB0_893
	s_mov_b64 s[6:7], s[0:1]
	s_load_dwordx2 s[6:7], s[6:7], 0xa0
	s_lshl_b64 s[22:23], s[72:73], 13
	s_lshl_b64 s[28:29], s[72:73], 24
	s_lshl_b32 s5, s70, 1
	v_lshlrev_b32_e32 v82, 1, v82
	s_waitcnt lgkmcnt(0)
	s_add_u32 s28, s6, s28
	s_addc_u32 s29, s7, s29
	s_add_u32 s28, s28, s5
	v_mov_b32_e32 v83, v146
	s_addc_u32 s29, s29, 0
	v_lshl_add_u64 v[82:83], s[28:29], 0, v[82:83]
	v_lshl_add_u64 v[82:83], s[8:9], 1, v[82:83]
	s_add_u32 s8, s68, s22
	s_addc_u32 s9, s69, s23
	s_add_u32 s8, s8, s13
	s_addc_u32 s9, s9, s14
	v_mov_b32_e32 v187, v146
	s_lshl_b64 s[8:9], s[8:9], 11
	v_lshl_add_u64 v[86:87], s[28:29], 0, v[186:187]
	s_add_u32 s6, s6, s8
	v_lshl_add_u64 v[86:87], s[78:79], 1, v[86:87]
	v_mov_b32_e32 v185, v146
	s_addc_u32 s7, s7, s9
	v_lshl_add_u64 v[84:85], v[82:83], 0, s[16:17]
	v_lshl_add_u64 v[86:87], v[86:87], 0, v[184:185]
	s_add_u32 s6, s6, s5
	s_mov_b32 m0, s25
	s_nop 0
	global_load_lds_dwordx4 v[84:85], off
	v_lshl_add_u64 v[88:89], v[86:87], 0, s[58:59]
	s_addc_u32 s7, s7, 0
	s_mov_b32 m0, s55
	s_nop 0
	global_load_lds_dwordx4 v[88:89], off
	s_mov_b64 s[8:9], 0xc800080
	s_mov_b32 m0, s54
	v_lshl_add_u64 v[84:85], v[86:87], 0, s[8:9]
	global_load_lds_dwordx4 v[84:85], off
	s_cmp_lg_u32 0, -1
	s_cselect_b32 s5, 0, 0
	s_mov_b64 s[8:9], 0x8820000
	s_add_i32 s5, s5, s24
	v_lshl_add_u64 v[84:85], v[82:83], 0, s[8:9]
	s_add_i32 s8, s5, 0x2000
	s_mov_b32 m0, s8
	s_nop 0
	global_load_lds_dwordx4 v[84:85], off
	s_mov_b64 s[8:9], 0xc820000
	v_lshl_add_u64 v[84:85], v[86:87], 0, s[8:9]
	s_add_i32 s8, s5, 0x8000
	s_mov_b32 m0, s8
	s_nop 0
	global_load_lds_dwordx4 v[84:85], off
	s_mov_b64 s[8:9], 0xc820080
	v_lshl_add_u64 v[84:85], v[86:87], 0, s[8:9]
	s_add_i32 s8, s5, 0x10000
	s_mov_b32 m0, s8
	s_nop 0
	global_load_lds_dwordx4 v[84:85], off
	s_mov_b64 s[8:9], 0x8840000
	v_lshl_add_u64 v[82:83], v[82:83], 0, s[8:9]
	s_addk_i32 s5, 0x4000
	s_mov_b32 m0, s5
	s_nop 0
	global_load_lds_dwordx4 v[82:83], off
	v_lshlrev_b32_e32 v82, 11, v207
	v_lshl_or_b32 v82, v208, 4, v82
	v_mov_b32_e32 v83, v146
	v_lshl_add_u64 v[82:83], s[6:7], 0, v[82:83]
	v_lshl_add_u64 v[84:85], v[82:83], 0, s[30:31]
	v_add_co_u32_e32 v82, vcc, s97, v82
	s_nop 1
	v_addc_co_u32_e32 v83, vcc, 0, v83, vcc
	global_load_dwordx4 v[152:155], v[84:85], off offset:32
	global_load_dwordx4 v[156:159], v[84:85], off offset:64
	global_load_dwordx4 v[148:151], v[82:83], off
	global_load_dwordx4 v[160:163], v[84:85], off offset:96

.LBB0_966:
	ds_read_b128 v[128:131], v189
	ds_read_b128 v[132:135], v189 offset:1024
	ds_read_b128 v[136:139], v189 offset:2048
	ds_read_b128 v[140:143], v189 offset:3072
	ds_read_b128 v[144:147], v190
	ds_read_b128 v[148:151], v190 offset:1024
	ds_read_b128 v[168:171], v190 offset:2048
	ds_read_b128 v[172:175], v190 offset:3072
	s_add_u32 s4, s22, 0xfffc0080
	s_addc_u32 s5, s23, -1
	s_cmp_eq_u32 s58, 12
	s_cselect_b32 s43, s35, s5
	s_cselect_b32 s42, s41, s4
	s_cselect_b32 s5, s31, s57
	s_cselect_b32 s4, s55, s56
	v_lshl_add_u64 v[184:185], s[22:23], 0, v[160:161]
	s_add_i32 m0, s46, 0xc000
	ds_read_b128 v[176:179], v191
	ds_read_b128 v[180:183], v191 offset:1024
	ds_read_b128 v[192:195], v191 offset:2048
	ds_read_b128 v[198:201], v191 offset:3072
	ds_read_b128 v[204:207], v191 offset:4096
	ds_read_b128 v[208:211], v191 offset:5120
	ds_read_b128 v[212:215], v191 offset:6144
	ds_read_b128 v[216:219], v191 offset:7168
	global_load_lds_dwordx4 v[184:185], off
	s_add_i32 m0, s46, 0xe000
	v_lshl_add_u64 v[184:185], s[22:23], 0, v[162:163]
	global_load_lds_dwordx4 v[184:185], off
	s_waitcnt vmcnt(8) lgkmcnt(0)
	s_setprio 1
	s_barrier
	v_mfma_f32_16x16x32_bf16 v[124:127], v[128:131], v[176:179], v[124:127]
	v_mfma_f32_16x16x32_bf16 v[120:123], v[136:139], v[176:179], v[120:123]
	v_mfma_f32_16x16x32_bf16 v[108:111], v[128:131], v[192:195], v[108:111]
	v_mfma_f32_16x16x32_bf16 v[104:107], v[136:139], v[192:195], v[104:107]
	v_mfma_f32_16x16x32_bf16 v[92:95], v[128:131], v[204:207], v[92:95]
	v_mfma_f32_16x16x32_bf16 v[88:91], v[136:139], v[204:207], v[88:91]
	v_mfma_f32_16x16x32_bf16 v[76:79], v[128:131], v[212:215], v[76:79]
	v_mfma_f32_16x16x32_bf16 v[72:75], v[136:139], v[212:215], v[72:75]
	v_mfma_f32_16x16x32_bf16 v[124:127], v[132:135], v[180:183], v[124:127]
	v_mfma_f32_16x16x32_bf16 v[120:123], v[140:143], v[180:183], v[120:123]
	v_mfma_f32_16x16x32_bf16 v[108:111], v[132:135], v[198:201], v[108:111]
	v_mfma_f32_16x16x32_bf16 v[104:107], v[140:143], v[198:201], v[104:107]
	v_mfma_f32_16x16x32_bf16 v[92:95], v[132:135], v[208:211], v[92:95]
	v_mfma_f32_16x16x32_bf16 v[88:91], v[140:143], v[208:211], v[88:91]
	v_mfma_f32_16x16x32_bf16 v[76:79], v[132:135], v[216:219], v[76:79]
	v_mfma_f32_16x16x32_bf16 v[72:75], v[140:143], v[216:219], v[72:75]
	s_setprio 0
	s_setprio 1
	v_mfma_f32_16x16x32_bf16 v[116:119], v[144:147], v[176:179], v[116:119]
	v_mfma_f32_16x16x32_bf16 v[112:115], v[168:171], v[176:179], v[112:115]
	v_mfma_f32_16x16x32_bf16 v[100:103], v[144:147], v[192:195], v[100:103]
	v_mfma_f32_16x16x32_bf16 v[96:99], v[168:171], v[192:195], v[96:99]
	v_mfma_f32_16x16x32_bf16 v[84:87], v[144:147], v[204:207], v[84:87]
	v_mfma_f32_16x16x32_bf16 v[80:83], v[168:171], v[204:207], v[80:83]
	v_mfma_f32_16x16x32_bf16 v[68:71], v[144:147], v[212:215], v[68:71]
	v_mfma_f32_16x16x32_bf16 v[64:67], v[168:171], v[212:215], v[64:67]
	v_mfma_f32_16x16x32_bf16 v[116:119], v[148:151], v[180:183], v[116:119]
	v_mfma_f32_16x16x32_bf16 v[112:115], v[172:175], v[180:183], v[112:115]
	v_mfma_f32_16x16x32_bf16 v[100:103], v[148:151], v[198:201], v[100:103]
	v_mfma_f32_16x16x32_bf16 v[96:99], v[172:175], v[198:201], v[96:99]
	v_mfma_f32_16x16x32_bf16 v[84:87], v[148:151], v[208:211], v[84:87]
	v_mfma_f32_16x16x32_bf16 v[80:83], v[172:175], v[208:211], v[80:83]
	v_mfma_f32_16x16x32_bf16 v[68:71], v[148:151], v[216:219], v[68:71]
	v_mfma_f32_16x16x32_bf16 v[64:67], v[172:175], v[216:219], v[64:67]
	s_setprio 0
	s_barrier
	s_add_i32 s59, s52, s45
	v_lshl_add_u64 v[184:185], s[4:5], 0, v[154:155]
	s_mov_b32 m0, s59
	ds_read_b128 v[176:179], v191 offset:16384
	ds_read_b128 v[180:183], v191 offset:17408
	ds_read_b128 v[192:195], v191 offset:18432
	ds_read_b128 v[198:201], v191 offset:19456
	ds_read_b128 v[204:207], v191 offset:20480
	ds_read_b128 v[208:211], v191 offset:21504
	ds_read_b128 v[212:215], v191 offset:22528
	ds_read_b128 v[216:219], v191 offset:23552
	global_load_lds_dwordx4 v[184:185], off
	s_add_i32 m0, s59, 0x2000
	s_add_u32 s60, s4, 0x40000
	v_lshl_add_u64 v[220:221], s[4:5], 0, v[158:159]
	s_addc_u32 s61, s5, 0
	s_add_i32 s59, s53, s45
	global_load_lds_dwordx4 v[220:221], off
	v_lshl_add_u64 v[222:223], s[60:61], 0, v[154:155]
	s_mov_b32 m0, s59
	v_lshl_add_u64 v[224:225], s[42:43], 0, v[156:157]
	global_load_lds_dwordx4 v[222:223], off
	s_add_i32 m0, s59, 0x2000
	v_lshl_add_u64 v[222:223], s[60:61], 0, v[158:159]
	global_load_lds_dwordx4 v[222:223], off
	s_mov_b32 m0, s46
	v_lshl_add_u64 v[222:223], s[42:43], 0, v[152:153]
	global_load_lds_dwordx4 v[222:223], off
	s_mov_b32 m0, s33
	s_nop 0
	global_load_lds_dwordx4 v[224:225], off
	s_waitcnt vmcnt(8) lgkmcnt(0)
	s_setprio 1
	s_barrier
	v_mfma_f32_16x16x32_bf16 v[60:63], v[128:131], v[176:179], v[60:63]
	v_mfma_f32_16x16x32_bf16 v[56:59], v[136:139], v[176:179], v[56:59]
	v_mfma_f32_16x16x32_bf16 v[44:47], v[128:131], v[192:195], v[44:47]
	v_mfma_f32_16x16x32_bf16 v[40:43], v[136:139], v[192:195], v[40:43]
	v_mfma_f32_16x16x32_bf16 v[28:31], v[128:131], v[204:207], v[28:31]
	v_mfma_f32_16x16x32_bf16 v[24:27], v[136:139], v[204:207], v[24:27]
	v_mfma_f32_16x16x32_bf16 v[12:15], v[128:131], v[212:215], v[12:15]
	v_mfma_f32_16x16x32_bf16 v[8:11], v[136:139], v[212:215], v[8:11]
	v_mfma_f32_16x16x32_bf16 v[60:63], v[132:135], v[180:183], v[60:63]
	v_mfma_f32_16x16x32_bf16 v[56:59], v[140:143], v[180:183], v[56:59]
	v_mfma_f32_16x16x32_bf16 v[44:47], v[132:135], v[198:201], v[44:47]
	v_mfma_f32_16x16x32_bf16 v[40:43], v[140:143], v[198:201], v[40:43]
	v_mfma_f32_16x16x32_bf16 v[28:31], v[132:135], v[208:211], v[28:31]
	v_mfma_f32_16x16x32_bf16 v[24:27], v[140:143], v[208:211], v[24:27]
	v_mfma_f32_16x16x32_bf16 v[12:15], v[132:135], v[216:219], v[12:15]
	v_mfma_f32_16x16x32_bf16 v[8:11], v[140:143], v[216:219], v[8:11]
	s_setprio 0
	s_setprio 1
	v_mfma_f32_16x16x32_bf16 v[52:55], v[144:147], v[176:179], v[52:55]
	v_mfma_f32_16x16x32_bf16 v[48:51], v[168:171], v[176:179], v[48:51]
	v_mfma_f32_16x16x32_bf16 v[36:39], v[144:147], v[192:195], v[36:39]
	v_mfma_f32_16x16x32_bf16 v[32:35], v[168:171], v[192:195], v[32:35]
	v_mfma_f32_16x16x32_bf16 v[20:23], v[144:147], v[204:207], v[20:23]
	v_mfma_f32_16x16x32_bf16 v[16:19], v[168:171], v[204:207], v[16:19]
	v_mfma_f32_16x16x32_bf16 v[4:7], v[144:147], v[212:215], v[4:7]
	v_mfma_f32_16x16x32_bf16 v[0:3], v[168:171], v[212:215], v[0:3]
	v_mfma_f32_16x16x32_bf16 v[52:55], v[148:151], v[180:183], v[52:55]
	v_mfma_f32_16x16x32_bf16 v[48:51], v[172:175], v[180:183], v[48:51]
	v_mfma_f32_16x16x32_bf16 v[36:39], v[148:151], v[198:201], v[36:39]
	v_mfma_f32_16x16x32_bf16 v[32:35], v[172:175], v[198:201], v[32:35]
	v_mfma_f32_16x16x32_bf16 v[20:23], v[148:151], v[208:211], v[20:23]
	v_mfma_f32_16x16x32_bf16 v[16:19], v[172:175], v[208:211], v[16:19]
	v_mfma_f32_16x16x32_bf16 v[4:7], v[148:151], v[216:219], v[4:7]
	v_mfma_f32_16x16x32_bf16 v[0:3], v[172:175], v[216:219], v[0:3]
	s_setprio 0
	s_barrier
	s_add_i32 s59, 0, 0x18000
	s_add_i32 s60, 0, 0x1c000
	v_add_u32_e32 v140, s59, v187
	v_add_u32_e32 v172, s60, v187
	ds_read_b128 v[128:131], v140
	ds_read_b128 v[132:135], v140 offset:1024
	ds_read_b128 v[136:139], v140 offset:2048
	ds_read_b128 v[140:143], v140 offset:3072
	ds_read_b128 v[144:147], v172
	ds_read_b128 v[148:151], v172 offset:1024
	ds_read_b128 v[168:171], v172 offset:2048
	ds_read_b128 v[172:175], v172 offset:3072
	s_add_u32 s42, s42, 0x40000
	s_addc_u32 s43, s43, 0
	s_mov_b32 m0, s47
	v_lshl_add_u64 v[226:227], s[42:43], 0, v[152:153]
	ds_read_b128 v[176:179], v191 offset:32768
	ds_read_b128 v[180:183], v191 offset:33792
	ds_read_b128 v[192:195], v191 offset:34816
	ds_read_b128 v[198:201], v191 offset:35840
	ds_read_b128 v[204:207], v191 offset:36864
	ds_read_b128 v[208:211], v191 offset:37888
	ds_read_b128 v[212:215], v191 offset:38912
	ds_read_b128 v[216:219], v191 offset:39936
	global_load_lds_dwordx4 v[226:227], off
	s_mov_b32 m0, s48
	v_lshl_add_u64 v[226:227], s[42:43], 0, v[156:157]
	global_load_lds_dwordx4 v[226:227], off
	s_waitcnt vmcnt(8) lgkmcnt(0)
	s_setprio 1
	s_barrier
	v_mfma_f32_16x16x32_bf16 v[124:127], v[128:131], v[176:179], v[124:127]
	v_mfma_f32_16x16x32_bf16 v[120:123], v[136:139], v[176:179], v[120:123]
	v_mfma_f32_16x16x32_bf16 v[108:111], v[128:131], v[192:195], v[108:111]
	v_mfma_f32_16x16x32_bf16 v[104:107], v[136:139], v[192:195], v[104:107]
	v_mfma_f32_16x16x32_bf16 v[92:95], v[128:131], v[204:207], v[92:95]
	v_mfma_f32_16x16x32_bf16 v[88:91], v[136:139], v[204:207], v[88:91]
	v_mfma_f32_16x16x32_bf16 v[76:79], v[128:131], v[212:215], v[76:79]
	v_mfma_f32_16x16x32_bf16 v[72:75], v[136:139], v[212:215], v[72:75]
	v_mfma_f32_16x16x32_bf16 v[124:127], v[132:135], v[180:183], v[124:127]
	v_mfma_f32_16x16x32_bf16 v[120:123], v[140:143], v[180:183], v[120:123]
	v_mfma_f32_16x16x32_bf16 v[108:111], v[132:135], v[198:201], v[108:111]
	v_mfma_f32_16x16x32_bf16 v[104:107], v[140:143], v[198:201], v[104:107]
	v_mfma_f32_16x16x32_bf16 v[92:95], v[132:135], v[208:211], v[92:95]
	v_mfma_f32_16x16x32_bf16 v[88:91], v[140:143], v[208:211], v[88:91]
	v_mfma_f32_16x16x32_bf16 v[76:79], v[132:135], v[216:219], v[76:79]
	v_mfma_f32_16x16x32_bf16 v[72:75], v[140:143], v[216:219], v[72:75]
	s_setprio 0
	s_setprio 1
	v_mfma_f32_16x16x32_bf16 v[116:119], v[144:147], v[176:179], v[116:119]
	v_mfma_f32_16x16x32_bf16 v[112:115], v[168:171], v[176:179], v[112:115]
	v_mfma_f32_16x16x32_bf16 v[100:103], v[144:147], v[192:195], v[100:103]
	v_mfma_f32_16x16x32_bf16 v[96:99], v[168:171], v[192:195], v[96:99]
	v_mfma_f32_16x16x32_bf16 v[84:87], v[144:147], v[204:207], v[84:87]
	v_mfma_f32_16x16x32_bf16 v[80:83], v[168:171], v[204:207], v[80:83]
	v_mfma_f32_16x16x32_bf16 v[68:71], v[144:147], v[212:215], v[68:71]
	v_mfma_f32_16x16x32_bf16 v[64:67], v[168:171], v[212:215], v[64:67]
	v_mfma_f32_16x16x32_bf16 v[116:119], v[148:151], v[180:183], v[116:119]
	v_mfma_f32_16x16x32_bf16 v[112:115], v[172:175], v[180:183], v[112:115]
	v_mfma_f32_16x16x32_bf16 v[100:103], v[148:151], v[198:201], v[100:103]
	v_mfma_f32_16x16x32_bf16 v[96:99], v[172:175], v[198:201], v[96:99]
	v_mfma_f32_16x16x32_bf16 v[84:87], v[148:151], v[208:211], v[84:87]
	v_mfma_f32_16x16x32_bf16 v[80:83], v[172:175], v[208:211], v[80:83]
	v_mfma_f32_16x16x32_bf16 v[68:71], v[148:151], v[216:219], v[68:71]
	v_mfma_f32_16x16x32_bf16 v[64:67], v[172:175], v[216:219], v[64:67]
	s_setprio 0
	s_barrier
	s_add_i32 s42, s59, s45
	v_lshl_add_u64 v[184:185], v[184:185], 0, s[26:27]
	s_mov_b32 m0, s42
	ds_read_b128 v[176:179], v191 offset:49152
	ds_read_b128 v[180:183], v191 offset:50176
	ds_read_b128 v[192:195], v191 offset:51200
	ds_read_b128 v[198:201], v191 offset:52224
	ds_read_b128 v[204:207], v191 offset:53248
	ds_read_b128 v[208:211], v191 offset:54272
	ds_read_b128 v[212:215], v191 offset:55296
	ds_read_b128 v[216:219], v191 offset:56320
	global_load_lds_dwordx4 v[184:185], off
	s_add_i32 m0, s42, 0x2000
	s_add_u32 s4, s4, 0x40080
	v_lshl_add_u64 v[184:185], v[220:221], 0, s[26:27]
	s_addc_u32 s5, s5, 0
	s_add_i32 s42, s60, s45
	global_load_lds_dwordx4 v[184:185], off
	s_mov_b32 m0, s42
	v_lshl_add_u64 v[184:185], s[4:5], 0, v[154:155]
	global_load_lds_dwordx4 v[184:185], off
	s_add_i32 m0, s42, 0x2000
	v_lshl_add_u64 v[184:185], s[4:5], 0, v[158:159]
	global_load_lds_dwordx4 v[184:185], off
	s_mov_b32 m0, s50
	v_lshl_add_u64 v[184:185], v[222:223], 0, s[26:27]
	global_load_lds_dwordx4 v[184:185], off
	s_mov_b32 m0, s51
	v_lshl_add_u64 v[184:185], v[224:225], 0, s[26:27]
	global_load_lds_dwordx4 v[184:185], off
	s_waitcnt vmcnt(8) lgkmcnt(0)
	s_setprio 1
	s_barrier
	v_mfma_f32_16x16x32_bf16 v[60:63], v[128:131], v[176:179], v[60:63]
	v_mfma_f32_16x16x32_bf16 v[56:59], v[136:139], v[176:179], v[56:59]
	v_mfma_f32_16x16x32_bf16 v[44:47], v[128:131], v[192:195], v[44:47]
	v_mfma_f32_16x16x32_bf16 v[40:43], v[136:139], v[192:195], v[40:43]
	v_mfma_f32_16x16x32_bf16 v[28:31], v[128:131], v[204:207], v[28:31]
	v_mfma_f32_16x16x32_bf16 v[24:27], v[136:139], v[204:207], v[24:27]
	v_mfma_f32_16x16x32_bf16 v[12:15], v[128:131], v[212:215], v[12:15]
	v_mfma_f32_16x16x32_bf16 v[8:11], v[136:139], v[212:215], v[8:11]
	v_mfma_f32_16x16x32_bf16 v[60:63], v[132:135], v[180:183], v[60:63]
	v_mfma_f32_16x16x32_bf16 v[56:59], v[140:143], v[180:183], v[56:59]
	v_mfma_f32_16x16x32_bf16 v[44:47], v[132:135], v[198:201], v[44:47]
	v_mfma_f32_16x16x32_bf16 v[40:43], v[140:143], v[198:201], v[40:43]
	v_mfma_f32_16x16x32_bf16 v[28:31], v[132:135], v[208:211], v[28:31]
	v_mfma_f32_16x16x32_bf16 v[24:27], v[140:143], v[208:211], v[24:27]
	v_mfma_f32_16x16x32_bf16 v[12:15], v[132:135], v[216:219], v[12:15]
	v_mfma_f32_16x16x32_bf16 v[8:11], v[140:143], v[216:219], v[8:11]
	s_setprio 0
	s_setprio 1
	v_mfma_f32_16x16x32_bf16 v[52:55], v[144:147], v[176:179], v[52:55]
	v_mfma_f32_16x16x32_bf16 v[48:51], v[168:171], v[176:179], v[48:51]
	v_mfma_f32_16x16x32_bf16 v[36:39], v[144:147], v[192:195], v[36:39]
	v_mfma_f32_16x16x32_bf16 v[32:35], v[168:171], v[192:195], v[32:35]
	v_mfma_f32_16x16x32_bf16 v[20:23], v[144:147], v[204:207], v[20:23]
	v_mfma_f32_16x16x32_bf16 v[16:19], v[168:171], v[204:207], v[16:19]
	v_mfma_f32_16x16x32_bf16 v[4:7], v[144:147], v[212:215], v[4:7]
	v_mfma_f32_16x16x32_bf16 v[0:3], v[168:171], v[212:215], v[0:3]
	v_mfma_f32_16x16x32_bf16 v[52:55], v[148:151], v[180:183], v[52:55]
	v_mfma_f32_16x16x32_bf16 v[48:51], v[172:175], v[180:183], v[48:51]
	v_mfma_f32_16x16x32_bf16 v[36:39], v[148:151], v[198:201], v[36:39]
	v_mfma_f32_16x16x32_bf16 v[32:35], v[172:175], v[198:201], v[32:35]
	v_mfma_f32_16x16x32_bf16 v[20:23], v[148:151], v[208:211], v[20:23]
	v_mfma_f32_16x16x32_bf16 v[16:19], v[172:175], v[208:211], v[16:19]
	v_mfma_f32_16x16x32_bf16 v[4:7], v[148:151], v[216:219], v[4:7]
	v_mfma_f32_16x16x32_bf16 v[0:3], v[172:175], v[216:219], v[0:3]
	s_setprio 0
	s_add_i32 s58, s58, 2
	s_add_u32 s22, s22, 0x100
	s_addc_u32 s23, s23, 0
	s_add_u32 s56, s56, 0x100
	s_addc_u32 s57, s57, 0
	s_cmp_gt_u32 s58, 13
	s_barrier
	s_cbranch_scc0 .LBB0_966
	s_and_b64 vcc, exec, s[28:29]
	s_cbranch_vccz .LBB0_969
	s_barrier

.LBB0_1048:
	ds_read_b128 v[146:149], v169
	ds_read_b128 v[150:153], v169 offset:1024
	ds_read_b128 v[154:157], v169 offset:2048
	ds_read_b128 v[160:163], v169 offset:3072
	ds_read_b128 v[178:181], v171
	ds_read_b128 v[182:185], v171 offset:1024
	ds_read_b128 v[186:189], v171 offset:2048
	ds_read_b128 v[190:193], v171 offset:3072
	s_add_u32 s4, s10, 0xfffc0080
	s_addc_u32 s5, s11, -1
	s_cmp_eq_u32 s55, 12
	s_cselect_b32 s13, s9, s5
	s_cselect_b32 s12, s31, s4
	s_cselect_b32 s5, s29, s54
	s_cselect_b32 s4, s52, s53
	v_lshl_add_u64 v[194:195], s[10:11], 0, v[138:139]
	s_add_i32 m0, s41, 0xc000
	ds_read_b128 v[198:201], v173
	ds_read_b128 v[204:207], v173 offset:1024
	ds_read_b128 v[208:211], v173 offset:2048
	ds_read_b128 v[212:215], v173 offset:3072
	ds_read_b128 v[216:219], v173 offset:4096
	ds_read_b128 v[220:223], v173 offset:5120
	ds_read_b128 v[224:227], v173 offset:6144
	ds_read_b128 v[228:231], v173 offset:7168
	global_load_lds_dwordx4 v[194:195], off
	s_add_i32 m0, s41, 0xe000
	v_lshl_add_u64 v[194:195], s[10:11], 0, v[140:141]
	global_load_lds_dwordx4 v[194:195], off
	s_waitcnt vmcnt(8) lgkmcnt(0)
	s_setprio 1
	s_barrier
	v_mfma_f32_16x16x32_bf16 v[124:127], v[146:149], v[198:201], v[124:127]
	v_mfma_f32_16x16x32_bf16 v[116:119], v[154:157], v[198:201], v[116:119]
	v_mfma_f32_16x16x32_bf16 v[108:111], v[146:149], v[208:211], v[108:111]
	v_mfma_f32_16x16x32_bf16 v[100:103], v[154:157], v[208:211], v[100:103]
	v_mfma_f32_16x16x32_bf16 v[92:95], v[146:149], v[216:219], v[92:95]
	v_mfma_f32_16x16x32_bf16 v[84:87], v[154:157], v[216:219], v[84:87]
	v_mfma_f32_16x16x32_bf16 v[76:79], v[146:149], v[224:227], v[76:79]
	v_mfma_f32_16x16x32_bf16 v[68:71], v[154:157], v[224:227], v[68:71]
	v_mfma_f32_16x16x32_bf16 v[124:127], v[150:153], v[204:207], v[124:127]
	v_mfma_f32_16x16x32_bf16 v[116:119], v[160:163], v[204:207], v[116:119]
	v_mfma_f32_16x16x32_bf16 v[108:111], v[150:153], v[212:215], v[108:111]
	v_mfma_f32_16x16x32_bf16 v[100:103], v[160:163], v[212:215], v[100:103]
	v_mfma_f32_16x16x32_bf16 v[92:95], v[150:153], v[220:223], v[92:95]
	v_mfma_f32_16x16x32_bf16 v[84:87], v[160:163], v[220:223], v[84:87]
	v_mfma_f32_16x16x32_bf16 v[76:79], v[150:153], v[228:231], v[76:79]
	v_mfma_f32_16x16x32_bf16 v[68:71], v[160:163], v[228:231], v[68:71]
	s_setprio 0
	s_setprio 1
	v_mfma_f32_16x16x32_bf16 v[120:123], v[178:181], v[198:201], v[120:123]
	v_mfma_f32_16x16x32_bf16 v[112:115], v[186:189], v[198:201], v[112:115]
	v_mfma_f32_16x16x32_bf16 v[104:107], v[178:181], v[208:211], v[104:107]
	v_mfma_f32_16x16x32_bf16 v[96:99], v[186:189], v[208:211], v[96:99]
	v_mfma_f32_16x16x32_bf16 v[88:91], v[178:181], v[216:219], v[88:91]
	v_mfma_f32_16x16x32_bf16 v[80:83], v[186:189], v[216:219], v[80:83]
	v_mfma_f32_16x16x32_bf16 v[72:75], v[178:181], v[224:227], v[72:75]
	v_mfma_f32_16x16x32_bf16 v[64:67], v[186:189], v[224:227], v[64:67]
	v_mfma_f32_16x16x32_bf16 v[120:123], v[182:185], v[204:207], v[120:123]
	v_mfma_f32_16x16x32_bf16 v[112:115], v[190:193], v[204:207], v[112:115]
	v_mfma_f32_16x16x32_bf16 v[104:107], v[182:185], v[212:215], v[104:107]
	v_mfma_f32_16x16x32_bf16 v[96:99], v[190:193], v[212:215], v[96:99]
	v_mfma_f32_16x16x32_bf16 v[88:91], v[182:185], v[220:223], v[88:91]
	v_mfma_f32_16x16x32_bf16 v[80:83], v[190:193], v[220:223], v[80:83]
	v_mfma_f32_16x16x32_bf16 v[72:75], v[182:185], v[228:231], v[72:75]
	v_mfma_f32_16x16x32_bf16 v[64:67], v[190:193], v[228:231], v[64:67]
	s_setprio 0
	s_barrier
	s_add_i32 s56, s48, s39
	v_lshl_add_u64 v[194:195], s[4:5], 0, v[132:133]
	s_mov_b32 m0, s56
	ds_read_b128 v[198:201], v173 offset:16384
	ds_read_b128 v[204:207], v173 offset:17408
	ds_read_b128 v[208:211], v173 offset:18432
	ds_read_b128 v[212:215], v173 offset:19456
	ds_read_b128 v[216:219], v173 offset:20480
	ds_read_b128 v[220:223], v173 offset:21504
	ds_read_b128 v[224:227], v173 offset:22528
	ds_read_b128 v[228:231], v173 offset:23552
	global_load_lds_dwordx4 v[194:195], off
	s_add_i32 m0, s56, 0x2000
	s_add_u32 s56, s4, 0x40000
	v_lshl_add_u64 v[232:233], s[4:5], 0, v[128:129]
	s_addc_u32 s57, s5, 0
	s_add_i32 s58, s49, s39
	global_load_lds_dwordx4 v[232:233], off
	v_lshl_add_u64 v[234:235], s[56:57], 0, v[132:133]
	s_mov_b32 m0, s58
	v_lshl_add_u64 v[236:237], s[12:13], 0, v[130:131]
	global_load_lds_dwordx4 v[234:235], off
	s_add_i32 m0, s58, 0x2000
	v_lshl_add_u64 v[234:235], s[56:57], 0, v[128:129]
	global_load_lds_dwordx4 v[234:235], off
	s_mov_b32 m0, s41
	v_lshl_add_u64 v[234:235], s[12:13], 0, v[134:135]
	global_load_lds_dwordx4 v[234:235], off
	s_mov_b32 m0, s42
	s_nop 0
	global_load_lds_dwordx4 v[236:237], off
	s_waitcnt vmcnt(8) lgkmcnt(0)
	s_setprio 1
	s_barrier
	v_mfma_f32_16x16x32_bf16 v[60:63], v[146:149], v[198:201], v[60:63]
	v_mfma_f32_16x16x32_bf16 v[52:55], v[154:157], v[198:201], v[52:55]
	v_mfma_f32_16x16x32_bf16 v[44:47], v[146:149], v[208:211], v[44:47]
	v_mfma_f32_16x16x32_bf16 v[36:39], v[154:157], v[208:211], v[36:39]
	v_mfma_f32_16x16x32_bf16 v[28:31], v[146:149], v[216:219], v[28:31]
	v_mfma_f32_16x16x32_bf16 v[20:23], v[154:157], v[216:219], v[20:23]
	v_mfma_f32_16x16x32_bf16 v[12:15], v[146:149], v[224:227], v[12:15]
	v_mfma_f32_16x16x32_bf16 v[4:7], v[154:157], v[224:227], v[4:7]
	v_mfma_f32_16x16x32_bf16 v[60:63], v[150:153], v[204:207], v[60:63]
	v_mfma_f32_16x16x32_bf16 v[52:55], v[160:163], v[204:207], v[52:55]
	v_mfma_f32_16x16x32_bf16 v[44:47], v[150:153], v[212:215], v[44:47]
	v_mfma_f32_16x16x32_bf16 v[36:39], v[160:163], v[212:215], v[36:39]
	v_mfma_f32_16x16x32_bf16 v[28:31], v[150:153], v[220:223], v[28:31]
	v_mfma_f32_16x16x32_bf16 v[20:23], v[160:163], v[220:223], v[20:23]
	v_mfma_f32_16x16x32_bf16 v[12:15], v[150:153], v[228:231], v[12:15]
	v_mfma_f32_16x16x32_bf16 v[4:7], v[160:163], v[228:231], v[4:7]
	s_setprio 0
	s_setprio 1
	v_mfma_f32_16x16x32_bf16 v[56:59], v[178:181], v[198:201], v[56:59]
	v_mfma_f32_16x16x32_bf16 v[48:51], v[186:189], v[198:201], v[48:51]
	v_mfma_f32_16x16x32_bf16 v[40:43], v[178:181], v[208:211], v[40:43]
	v_mfma_f32_16x16x32_bf16 v[32:35], v[186:189], v[208:211], v[32:35]
	v_mfma_f32_16x16x32_bf16 v[24:27], v[178:181], v[216:219], v[24:27]
	v_mfma_f32_16x16x32_bf16 v[16:19], v[186:189], v[216:219], v[16:19]
	v_mfma_f32_16x16x32_bf16 v[8:11], v[178:181], v[224:227], v[8:11]
	v_mfma_f32_16x16x32_bf16 v[0:3], v[186:189], v[224:227], v[0:3]
	v_mfma_f32_16x16x32_bf16 v[56:59], v[182:185], v[204:207], v[56:59]
	v_mfma_f32_16x16x32_bf16 v[48:51], v[190:193], v[204:207], v[48:51]
	v_mfma_f32_16x16x32_bf16 v[40:43], v[182:185], v[212:215], v[40:43]
	v_mfma_f32_16x16x32_bf16 v[32:35], v[190:193], v[212:215], v[32:35]
	v_mfma_f32_16x16x32_bf16 v[24:27], v[182:185], v[220:223], v[24:27]
	v_mfma_f32_16x16x32_bf16 v[16:19], v[190:193], v[220:223], v[16:19]
	v_mfma_f32_16x16x32_bf16 v[8:11], v[182:185], v[228:231], v[8:11]
	v_mfma_f32_16x16x32_bf16 v[0:3], v[190:193], v[228:231], v[0:3]
	s_setprio 0
	s_barrier
	s_add_i32 s56, 0, 0x18000
	v_add_u32_e32 v158, s56, v165
	s_add_i32 s57, 0, 0x1c000
	ds_read_b128 v[146:149], v158
	ds_read_b128 v[150:153], v158 offset:1024
	ds_read_b128 v[154:157], v158 offset:2048
	ds_read_b128 v[160:163], v158 offset:3072
	v_add_u32_e32 v158, s57, v165
	ds_read_b128 v[178:181], v158
	ds_read_b128 v[182:185], v158 offset:1024
	ds_read_b128 v[186:189], v158 offset:2048
	ds_read_b128 v[190:193], v158 offset:3072
	s_add_u32 s12, s12, 0x40000
	s_addc_u32 s13, s13, 0
	s_mov_b32 m0, s43
	v_lshl_add_u64 v[238:239], s[12:13], 0, v[134:135]
	ds_read_b128 v[198:201], v173 offset:32768
	ds_read_b128 v[204:207], v173 offset:33792
	ds_read_b128 v[208:211], v173 offset:34816
	ds_read_b128 v[212:215], v173 offset:35840
	ds_read_b128 v[216:219], v173 offset:36864
	ds_read_b128 v[220:223], v173 offset:37888
	ds_read_b128 v[224:227], v173 offset:38912
	ds_read_b128 v[228:231], v173 offset:39936
	global_load_lds_dwordx4 v[238:239], off
	s_mov_b32 m0, s44
	v_lshl_add_u64 v[238:239], s[12:13], 0, v[130:131]
	global_load_lds_dwordx4 v[238:239], off
	s_waitcnt vmcnt(8) lgkmcnt(0)
	s_setprio 1
	s_barrier
	v_mfma_f32_16x16x32_bf16 v[124:127], v[146:149], v[198:201], v[124:127]
	v_mfma_f32_16x16x32_bf16 v[116:119], v[154:157], v[198:201], v[116:119]
	v_mfma_f32_16x16x32_bf16 v[108:111], v[146:149], v[208:211], v[108:111]
	v_mfma_f32_16x16x32_bf16 v[100:103], v[154:157], v[208:211], v[100:103]
	v_mfma_f32_16x16x32_bf16 v[92:95], v[146:149], v[216:219], v[92:95]
	v_mfma_f32_16x16x32_bf16 v[84:87], v[154:157], v[216:219], v[84:87]
	v_mfma_f32_16x16x32_bf16 v[76:79], v[146:149], v[224:227], v[76:79]
	v_mfma_f32_16x16x32_bf16 v[68:71], v[154:157], v[224:227], v[68:71]
	v_mfma_f32_16x16x32_bf16 v[124:127], v[150:153], v[204:207], v[124:127]
	v_mfma_f32_16x16x32_bf16 v[116:119], v[160:163], v[204:207], v[116:119]
	v_mfma_f32_16x16x32_bf16 v[108:111], v[150:153], v[212:215], v[108:111]
	v_mfma_f32_16x16x32_bf16 v[100:103], v[160:163], v[212:215], v[100:103]
	v_mfma_f32_16x16x32_bf16 v[92:95], v[150:153], v[220:223], v[92:95]
	v_mfma_f32_16x16x32_bf16 v[84:87], v[160:163], v[220:223], v[84:87]
	v_mfma_f32_16x16x32_bf16 v[76:79], v[150:153], v[228:231], v[76:79]
	v_mfma_f32_16x16x32_bf16 v[68:71], v[160:163], v[228:231], v[68:71]
	s_setprio 0
	s_setprio 1
	v_mfma_f32_16x16x32_bf16 v[120:123], v[178:181], v[198:201], v[120:123]
	v_mfma_f32_16x16x32_bf16 v[112:115], v[186:189], v[198:201], v[112:115]
	v_mfma_f32_16x16x32_bf16 v[104:107], v[178:181], v[208:211], v[104:107]
	v_mfma_f32_16x16x32_bf16 v[96:99], v[186:189], v[208:211], v[96:99]
	v_mfma_f32_16x16x32_bf16 v[88:91], v[178:181], v[216:219], v[88:91]
	v_mfma_f32_16x16x32_bf16 v[80:83], v[186:189], v[216:219], v[80:83]
	v_mfma_f32_16x16x32_bf16 v[72:75], v[178:181], v[224:227], v[72:75]
	v_mfma_f32_16x16x32_bf16 v[64:67], v[186:189], v[224:227], v[64:67]
	v_mfma_f32_16x16x32_bf16 v[120:123], v[182:185], v[204:207], v[120:123]
	v_mfma_f32_16x16x32_bf16 v[112:115], v[190:193], v[204:207], v[112:115]
	v_mfma_f32_16x16x32_bf16 v[104:107], v[182:185], v[212:215], v[104:107]
	v_mfma_f32_16x16x32_bf16 v[96:99], v[190:193], v[212:215], v[96:99]
	v_mfma_f32_16x16x32_bf16 v[88:91], v[182:185], v[220:223], v[88:91]
	v_mfma_f32_16x16x32_bf16 v[80:83], v[190:193], v[220:223], v[80:83]
	v_mfma_f32_16x16x32_bf16 v[72:75], v[182:185], v[228:231], v[72:75]
	v_mfma_f32_16x16x32_bf16 v[64:67], v[190:193], v[228:231], v[64:67]
	s_setprio 0
	s_barrier
	s_add_i32 s12, s56, s39
	v_lshl_add_u64 v[194:195], v[194:195], 0, s[24:25]
	s_mov_b32 m0, s12
	ds_read_b128 v[198:201], v173 offset:49152
	ds_read_b128 v[204:207], v173 offset:50176
	ds_read_b128 v[208:211], v173 offset:51200
	ds_read_b128 v[212:215], v173 offset:52224
	ds_read_b128 v[216:219], v173 offset:53248
	ds_read_b128 v[220:223], v173 offset:54272
	ds_read_b128 v[224:227], v173 offset:55296
	ds_read_b128 v[228:231], v173 offset:56320
	global_load_lds_dwordx4 v[194:195], off
	s_add_i32 m0, s12, 0x2000
	s_add_u32 s4, s4, 0x40080
	v_lshl_add_u64 v[194:195], v[232:233], 0, s[24:25]
	s_addc_u32 s5, s5, 0
	s_add_i32 s12, s57, s39
	global_load_lds_dwordx4 v[194:195], off
	s_mov_b32 m0, s12
	v_lshl_add_u64 v[194:195], s[4:5], 0, v[132:133]
	global_load_lds_dwordx4 v[194:195], off
	s_add_i32 m0, s12, 0x2000
	v_lshl_add_u64 v[194:195], s[4:5], 0, v[128:129]
	global_load_lds_dwordx4 v[194:195], off
	s_mov_b32 m0, s46
	v_lshl_add_u64 v[194:195], v[234:235], 0, s[24:25]
	global_load_lds_dwordx4 v[194:195], off
	s_mov_b32 m0, s47
	v_lshl_add_u64 v[194:195], v[236:237], 0, s[24:25]
	global_load_lds_dwordx4 v[194:195], off
	s_waitcnt vmcnt(8) lgkmcnt(0)
	s_setprio 1
	s_barrier
	v_mfma_f32_16x16x32_bf16 v[60:63], v[146:149], v[198:201], v[60:63]
	v_mfma_f32_16x16x32_bf16 v[52:55], v[154:157], v[198:201], v[52:55]
	v_mfma_f32_16x16x32_bf16 v[44:47], v[146:149], v[208:211], v[44:47]
	v_mfma_f32_16x16x32_bf16 v[36:39], v[154:157], v[208:211], v[36:39]
	v_mfma_f32_16x16x32_bf16 v[28:31], v[146:149], v[216:219], v[28:31]
	v_mfma_f32_16x16x32_bf16 v[20:23], v[154:157], v[216:219], v[20:23]
	v_mfma_f32_16x16x32_bf16 v[12:15], v[146:149], v[224:227], v[12:15]
	v_mfma_f32_16x16x32_bf16 v[4:7], v[154:157], v[224:227], v[4:7]
	v_mfma_f32_16x16x32_bf16 v[60:63], v[150:153], v[204:207], v[60:63]
	v_mfma_f32_16x16x32_bf16 v[52:55], v[160:163], v[204:207], v[52:55]
	v_mfma_f32_16x16x32_bf16 v[44:47], v[150:153], v[212:215], v[44:47]
	v_mfma_f32_16x16x32_bf16 v[36:39], v[160:163], v[212:215], v[36:39]
	v_mfma_f32_16x16x32_bf16 v[28:31], v[150:153], v[220:223], v[28:31]
	v_mfma_f32_16x16x32_bf16 v[20:23], v[160:163], v[220:223], v[20:23]
	v_mfma_f32_16x16x32_bf16 v[12:15], v[150:153], v[228:231], v[12:15]
	v_mfma_f32_16x16x32_bf16 v[4:7], v[160:163], v[228:231], v[4:7]
	s_setprio 0
	s_setprio 1
	v_mfma_f32_16x16x32_bf16 v[56:59], v[178:181], v[198:201], v[56:59]
	v_mfma_f32_16x16x32_bf16 v[48:51], v[186:189], v[198:201], v[48:51]
	v_mfma_f32_16x16x32_bf16 v[40:43], v[178:181], v[208:211], v[40:43]
	v_mfma_f32_16x16x32_bf16 v[32:35], v[186:189], v[208:211], v[32:35]
	v_mfma_f32_16x16x32_bf16 v[24:27], v[178:181], v[216:219], v[24:27]
	v_mfma_f32_16x16x32_bf16 v[16:19], v[186:189], v[216:219], v[16:19]
	v_mfma_f32_16x16x32_bf16 v[8:11], v[178:181], v[224:227], v[8:11]
	v_mfma_f32_16x16x32_bf16 v[0:3], v[186:189], v[224:227], v[0:3]
	v_mfma_f32_16x16x32_bf16 v[56:59], v[182:185], v[204:207], v[56:59]
	v_mfma_f32_16x16x32_bf16 v[48:51], v[190:193], v[204:207], v[48:51]
	v_mfma_f32_16x16x32_bf16 v[40:43], v[182:185], v[212:215], v[40:43]
	v_mfma_f32_16x16x32_bf16 v[32:35], v[190:193], v[212:215], v[32:35]
	v_mfma_f32_16x16x32_bf16 v[24:27], v[182:185], v[220:223], v[24:27]
	v_mfma_f32_16x16x32_bf16 v[16:19], v[190:193], v[220:223], v[16:19]
	v_mfma_f32_16x16x32_bf16 v[8:11], v[182:185], v[228:231], v[8:11]
	v_mfma_f32_16x16x32_bf16 v[0:3], v[190:193], v[228:231], v[0:3]
	s_setprio 0
	s_add_i32 s55, s55, 2
	s_add_u32 s10, s10, 0x100
	s_addc_u32 s11, s11, 0
	s_add_u32 s53, s53, 0x100
	s_addc_u32 s54, s54, 0
	s_cmp_gt_u32 s55, 13
	s_barrier
	s_cbranch_scc0 .LBB0_1048
	s_and_b64 vcc, exec, s[26:27]
	s_cbranch_vccz .LBB0_1051
	s_barrier

.LBB0_1124:
	ds_read_b128 v[128:131], v189
	ds_read_b128 v[132:135], v189 offset:1024
	ds_read_b128 v[136:139], v189 offset:2048
	ds_read_b128 v[140:143], v189 offset:3072
	ds_read_b128 v[144:147], v190
	ds_read_b128 v[148:151], v190 offset:1024
	ds_read_b128 v[168:171], v190 offset:2048
	ds_read_b128 v[172:175], v190 offset:3072
	s_add_u32 s34, s30, 0x100
	s_addc_u32 s35, s31, 0
	s_cmp_eq_u32 s56, 40
	s_cselect_b32 s39, s9, s35
	s_cselect_b32 s38, s8, s34
	s_cselect_b32 s37, s29, s55
	s_cselect_b32 s36, s28, s54
	v_lshl_add_u64 v[184:185], s[30:31], 0, v[160:161]
	s_add_i32 m0, s42, 0xc000
	ds_read_b128 v[176:179], v191
	ds_read_b128 v[180:183], v191 offset:1024
	ds_read_b128 v[192:195], v191 offset:2048
	ds_read_b128 v[198:201], v191 offset:3072
	ds_read_b128 v[204:207], v191 offset:4096
	ds_read_b128 v[208:211], v191 offset:5120
	ds_read_b128 v[212:215], v191 offset:6144
	ds_read_b128 v[216:219], v191 offset:7168
	global_load_lds_dwordx4 v[184:185], off
	s_add_i32 m0, s42, 0xe000
	v_lshl_add_u64 v[184:185], s[30:31], 0, v[162:163]
	global_load_lds_dwordx4 v[184:185], off
	s_waitcnt vmcnt(8) lgkmcnt(0)
	s_setprio 1
	s_barrier
	v_mfma_f32_16x16x32_bf16 v[124:127], v[128:131], v[176:179], v[124:127]
	v_mfma_f32_16x16x32_bf16 v[120:123], v[136:139], v[176:179], v[120:123]
	v_mfma_f32_16x16x32_bf16 v[108:111], v[128:131], v[192:195], v[108:111]
	v_mfma_f32_16x16x32_bf16 v[104:107], v[136:139], v[192:195], v[104:107]
	v_mfma_f32_16x16x32_bf16 v[92:95], v[128:131], v[204:207], v[92:95]
	v_mfma_f32_16x16x32_bf16 v[88:91], v[136:139], v[204:207], v[88:91]
	v_mfma_f32_16x16x32_bf16 v[76:79], v[128:131], v[212:215], v[76:79]
	v_mfma_f32_16x16x32_bf16 v[72:75], v[136:139], v[212:215], v[72:75]
	v_mfma_f32_16x16x32_bf16 v[124:127], v[132:135], v[180:183], v[124:127]
	v_mfma_f32_16x16x32_bf16 v[120:123], v[140:143], v[180:183], v[120:123]
	v_mfma_f32_16x16x32_bf16 v[108:111], v[132:135], v[198:201], v[108:111]
	v_mfma_f32_16x16x32_bf16 v[104:107], v[140:143], v[198:201], v[104:107]
	v_mfma_f32_16x16x32_bf16 v[92:95], v[132:135], v[208:211], v[92:95]
	v_mfma_f32_16x16x32_bf16 v[88:91], v[140:143], v[208:211], v[88:91]
	v_mfma_f32_16x16x32_bf16 v[76:79], v[132:135], v[216:219], v[76:79]
	v_mfma_f32_16x16x32_bf16 v[72:75], v[140:143], v[216:219], v[72:75]
	s_setprio 0
	s_setprio 1
	v_mfma_f32_16x16x32_bf16 v[116:119], v[144:147], v[176:179], v[116:119]
	v_mfma_f32_16x16x32_bf16 v[112:115], v[168:171], v[176:179], v[112:115]
	v_mfma_f32_16x16x32_bf16 v[100:103], v[144:147], v[192:195], v[100:103]
	v_mfma_f32_16x16x32_bf16 v[96:99], v[168:171], v[192:195], v[96:99]
	v_mfma_f32_16x16x32_bf16 v[84:87], v[144:147], v[204:207], v[84:87]
	v_mfma_f32_16x16x32_bf16 v[80:83], v[168:171], v[204:207], v[80:83]
	v_mfma_f32_16x16x32_bf16 v[68:71], v[144:147], v[212:215], v[68:71]
	v_mfma_f32_16x16x32_bf16 v[64:67], v[168:171], v[212:215], v[64:67]
	v_mfma_f32_16x16x32_bf16 v[116:119], v[148:151], v[180:183], v[116:119]
	v_mfma_f32_16x16x32_bf16 v[112:115], v[172:175], v[180:183], v[112:115]
	v_mfma_f32_16x16x32_bf16 v[100:103], v[148:151], v[198:201], v[100:103]
	v_mfma_f32_16x16x32_bf16 v[96:99], v[172:175], v[198:201], v[96:99]
	v_mfma_f32_16x16x32_bf16 v[84:87], v[148:151], v[208:211], v[84:87]
	v_mfma_f32_16x16x32_bf16 v[80:83], v[172:175], v[208:211], v[80:83]
	v_mfma_f32_16x16x32_bf16 v[68:71], v[148:151], v[216:219], v[68:71]
	v_mfma_f32_16x16x32_bf16 v[64:67], v[172:175], v[216:219], v[64:67]
	s_setprio 0
	s_barrier
	s_add_i32 s30, s48, s41
	v_lshl_add_u64 v[184:185], s[36:37], 0, v[154:155]
	s_mov_b32 m0, s30
	ds_read_b128 v[176:179], v191 offset:16384
	ds_read_b128 v[180:183], v191 offset:17408
	ds_read_b128 v[192:195], v191 offset:18432
	ds_read_b128 v[198:201], v191 offset:19456
	ds_read_b128 v[204:207], v191 offset:20480
	ds_read_b128 v[208:211], v191 offset:21504
	ds_read_b128 v[212:215], v191 offset:22528
	ds_read_b128 v[216:219], v191 offset:23552
	global_load_lds_dwordx4 v[184:185], off
	s_add_i32 m0, s30, 0x2000
	s_add_u32 s30, s36, 0xb0000
	v_lshl_add_u64 v[220:221], s[36:37], 0, v[158:159]
	s_addc_u32 s31, s37, 0
	s_add_i32 s57, s49, s41
	global_load_lds_dwordx4 v[220:221], off
	v_lshl_add_u64 v[222:223], s[30:31], 0, v[154:155]
	s_mov_b32 m0, s57
	v_lshl_add_u64 v[224:225], s[38:39], 0, v[156:157]
	global_load_lds_dwordx4 v[222:223], off
	s_add_i32 m0, s57, 0x2000
	v_lshl_add_u64 v[222:223], s[30:31], 0, v[158:159]
	global_load_lds_dwordx4 v[222:223], off
	s_mov_b32 m0, s42
	v_lshl_add_u64 v[222:223], s[38:39], 0, v[152:153]
	global_load_lds_dwordx4 v[222:223], off
	s_mov_b32 m0, s33
	s_nop 0
	global_load_lds_dwordx4 v[224:225], off
	s_waitcnt vmcnt(8) lgkmcnt(0)
	s_setprio 1
	s_barrier
	v_mfma_f32_16x16x32_bf16 v[60:63], v[128:131], v[176:179], v[60:63]
	v_mfma_f32_16x16x32_bf16 v[56:59], v[136:139], v[176:179], v[56:59]
	v_mfma_f32_16x16x32_bf16 v[44:47], v[128:131], v[192:195], v[44:47]
	v_mfma_f32_16x16x32_bf16 v[40:43], v[136:139], v[192:195], v[40:43]
	v_mfma_f32_16x16x32_bf16 v[28:31], v[128:131], v[204:207], v[28:31]
	v_mfma_f32_16x16x32_bf16 v[24:27], v[136:139], v[204:207], v[24:27]
	v_mfma_f32_16x16x32_bf16 v[12:15], v[128:131], v[212:215], v[12:15]
	v_mfma_f32_16x16x32_bf16 v[8:11], v[136:139], v[212:215], v[8:11]
	v_mfma_f32_16x16x32_bf16 v[60:63], v[132:135], v[180:183], v[60:63]
	v_mfma_f32_16x16x32_bf16 v[56:59], v[140:143], v[180:183], v[56:59]
	v_mfma_f32_16x16x32_bf16 v[44:47], v[132:135], v[198:201], v[44:47]
	v_mfma_f32_16x16x32_bf16 v[40:43], v[140:143], v[198:201], v[40:43]
	v_mfma_f32_16x16x32_bf16 v[28:31], v[132:135], v[208:211], v[28:31]
	v_mfma_f32_16x16x32_bf16 v[24:27], v[140:143], v[208:211], v[24:27]
	v_mfma_f32_16x16x32_bf16 v[12:15], v[132:135], v[216:219], v[12:15]
	v_mfma_f32_16x16x32_bf16 v[8:11], v[140:143], v[216:219], v[8:11]
	s_setprio 0
	s_setprio 1
	v_mfma_f32_16x16x32_bf16 v[52:55], v[144:147], v[176:179], v[52:55]
	v_mfma_f32_16x16x32_bf16 v[48:51], v[168:171], v[176:179], v[48:51]
	v_mfma_f32_16x16x32_bf16 v[36:39], v[144:147], v[192:195], v[36:39]
	v_mfma_f32_16x16x32_bf16 v[32:35], v[168:171], v[192:195], v[32:35]
	v_mfma_f32_16x16x32_bf16 v[20:23], v[144:147], v[204:207], v[20:23]
	v_mfma_f32_16x16x32_bf16 v[16:19], v[168:171], v[204:207], v[16:19]
	v_mfma_f32_16x16x32_bf16 v[4:7], v[144:147], v[212:215], v[4:7]
	v_mfma_f32_16x16x32_bf16 v[0:3], v[168:171], v[212:215], v[0:3]
	v_mfma_f32_16x16x32_bf16 v[52:55], v[148:151], v[180:183], v[52:55]
	v_mfma_f32_16x16x32_bf16 v[48:51], v[172:175], v[180:183], v[48:51]
	v_mfma_f32_16x16x32_bf16 v[36:39], v[148:151], v[198:201], v[36:39]
	v_mfma_f32_16x16x32_bf16 v[32:35], v[172:175], v[198:201], v[32:35]
	v_mfma_f32_16x16x32_bf16 v[20:23], v[148:151], v[208:211], v[20:23]
	v_mfma_f32_16x16x32_bf16 v[16:19], v[172:175], v[208:211], v[16:19]
	v_mfma_f32_16x16x32_bf16 v[4:7], v[148:151], v[216:219], v[4:7]
	v_mfma_f32_16x16x32_bf16 v[0:3], v[172:175], v[216:219], v[0:3]
	s_setprio 0
	s_barrier
	s_add_i32 s57, 0, 0x18000
	s_add_i32 s58, 0, 0x1c000
	v_add_u32_e32 v140, s57, v187
	v_add_u32_e32 v172, s58, v187
	ds_read_b128 v[128:131], v140
	ds_read_b128 v[132:135], v140 offset:1024
	ds_read_b128 v[136:139], v140 offset:2048
	ds_read_b128 v[140:143], v140 offset:3072
	ds_read_b128 v[144:147], v172
	ds_read_b128 v[148:151], v172 offset:1024
	ds_read_b128 v[168:171], v172 offset:2048
	ds_read_b128 v[172:175], v172 offset:3072
	s_add_u32 s30, s38, 0xb0000
	s_addc_u32 s31, s39, 0
	s_mov_b32 m0, s43
	v_lshl_add_u64 v[226:227], s[30:31], 0, v[152:153]
	ds_read_b128 v[176:179], v191 offset:32768
	ds_read_b128 v[180:183], v191 offset:33792
	ds_read_b128 v[192:195], v191 offset:34816
	ds_read_b128 v[198:201], v191 offset:35840
	ds_read_b128 v[204:207], v191 offset:36864
	ds_read_b128 v[208:211], v191 offset:37888
	ds_read_b128 v[212:215], v191 offset:38912
	ds_read_b128 v[216:219], v191 offset:39936
	global_load_lds_dwordx4 v[226:227], off
	s_mov_b32 m0, s44
	v_lshl_add_u64 v[226:227], s[30:31], 0, v[156:157]
	global_load_lds_dwordx4 v[226:227], off
	s_waitcnt vmcnt(8) lgkmcnt(0)
	s_setprio 1
	s_barrier
	v_mfma_f32_16x16x32_bf16 v[124:127], v[128:131], v[176:179], v[124:127]
	v_mfma_f32_16x16x32_bf16 v[120:123], v[136:139], v[176:179], v[120:123]
	v_mfma_f32_16x16x32_bf16 v[108:111], v[128:131], v[192:195], v[108:111]
	v_mfma_f32_16x16x32_bf16 v[104:107], v[136:139], v[192:195], v[104:107]
	v_mfma_f32_16x16x32_bf16 v[92:95], v[128:131], v[204:207], v[92:95]
	v_mfma_f32_16x16x32_bf16 v[88:91], v[136:139], v[204:207], v[88:91]
	v_mfma_f32_16x16x32_bf16 v[76:79], v[128:131], v[212:215], v[76:79]
	v_mfma_f32_16x16x32_bf16 v[72:75], v[136:139], v[212:215], v[72:75]
	v_mfma_f32_16x16x32_bf16 v[124:127], v[132:135], v[180:183], v[124:127]
	v_mfma_f32_16x16x32_bf16 v[120:123], v[140:143], v[180:183], v[120:123]
	v_mfma_f32_16x16x32_bf16 v[108:111], v[132:135], v[198:201], v[108:111]
	v_mfma_f32_16x16x32_bf16 v[104:107], v[140:143], v[198:201], v[104:107]
	v_mfma_f32_16x16x32_bf16 v[92:95], v[132:135], v[208:211], v[92:95]
	v_mfma_f32_16x16x32_bf16 v[88:91], v[140:143], v[208:211], v[88:91]
	v_mfma_f32_16x16x32_bf16 v[76:79], v[132:135], v[216:219], v[76:79]
	v_mfma_f32_16x16x32_bf16 v[72:75], v[140:143], v[216:219], v[72:75]
	s_setprio 0
	s_setprio 1
	v_mfma_f32_16x16x32_bf16 v[116:119], v[144:147], v[176:179], v[116:119]
	v_mfma_f32_16x16x32_bf16 v[112:115], v[168:171], v[176:179], v[112:115]
	v_mfma_f32_16x16x32_bf16 v[100:103], v[144:147], v[192:195], v[100:103]
	v_mfma_f32_16x16x32_bf16 v[96:99], v[168:171], v[192:195], v[96:99]
	v_mfma_f32_16x16x32_bf16 v[84:87], v[144:147], v[204:207], v[84:87]
	v_mfma_f32_16x16x32_bf16 v[80:83], v[168:171], v[204:207], v[80:83]
	v_mfma_f32_16x16x32_bf16 v[68:71], v[144:147], v[212:215], v[68:71]
	v_mfma_f32_16x16x32_bf16 v[64:67], v[168:171], v[212:215], v[64:67]
	v_mfma_f32_16x16x32_bf16 v[116:119], v[148:151], v[180:183], v[116:119]
	v_mfma_f32_16x16x32_bf16 v[112:115], v[172:175], v[180:183], v[112:115]
	v_mfma_f32_16x16x32_bf16 v[100:103], v[148:151], v[198:201], v[100:103]
	v_mfma_f32_16x16x32_bf16 v[96:99], v[172:175], v[198:201], v[96:99]
	v_mfma_f32_16x16x32_bf16 v[84:87], v[148:151], v[208:211], v[84:87]
	v_mfma_f32_16x16x32_bf16 v[80:83], v[172:175], v[208:211], v[80:83]
	v_mfma_f32_16x16x32_bf16 v[68:71], v[148:151], v[216:219], v[68:71]
	v_mfma_f32_16x16x32_bf16 v[64:67], v[172:175], v[216:219], v[64:67]
	s_setprio 0
	s_barrier
	s_add_i32 s30, s57, s41
	v_lshl_add_u64 v[184:185], v[184:185], 0, s[24:25]
	s_mov_b32 m0, s30
	ds_read_b128 v[176:179], v191 offset:49152
	ds_read_b128 v[180:183], v191 offset:50176
	ds_read_b128 v[192:195], v191 offset:51200
	ds_read_b128 v[198:201], v191 offset:52224
	ds_read_b128 v[204:207], v191 offset:53248
	ds_read_b128 v[208:211], v191 offset:54272
	ds_read_b128 v[212:215], v191 offset:55296
	ds_read_b128 v[216:219], v191 offset:56320
	global_load_lds_dwordx4 v[184:185], off
	s_add_i32 m0, s30, 0x2000
	s_add_u32 s30, s36, 0xb0080
	v_lshl_add_u64 v[184:185], v[220:221], 0, s[24:25]
	s_addc_u32 s31, s37, 0
	s_add_i32 s36, s58, s41
	global_load_lds_dwordx4 v[184:185], off
	s_mov_b32 m0, s36
	v_lshl_add_u64 v[184:185], s[30:31], 0, v[154:155]
	global_load_lds_dwordx4 v[184:185], off
	s_add_i32 m0, s36, 0x2000
	v_lshl_add_u64 v[184:185], s[30:31], 0, v[158:159]
	global_load_lds_dwordx4 v[184:185], off
	s_mov_b32 m0, s46
	v_lshl_add_u64 v[184:185], v[222:223], 0, s[24:25]
	global_load_lds_dwordx4 v[184:185], off
	s_mov_b32 m0, s47
	v_lshl_add_u64 v[184:185], v[224:225], 0, s[24:25]
	global_load_lds_dwordx4 v[184:185], off
	s_waitcnt vmcnt(8) lgkmcnt(0)
	s_setprio 1
	s_barrier
	v_mfma_f32_16x16x32_bf16 v[60:63], v[128:131], v[176:179], v[60:63]
	v_mfma_f32_16x16x32_bf16 v[56:59], v[136:139], v[176:179], v[56:59]
	v_mfma_f32_16x16x32_bf16 v[44:47], v[128:131], v[192:195], v[44:47]
	v_mfma_f32_16x16x32_bf16 v[40:43], v[136:139], v[192:195], v[40:43]
	v_mfma_f32_16x16x32_bf16 v[28:31], v[128:131], v[204:207], v[28:31]
	v_mfma_f32_16x16x32_bf16 v[24:27], v[136:139], v[204:207], v[24:27]
	v_mfma_f32_16x16x32_bf16 v[12:15], v[128:131], v[212:215], v[12:15]
	v_mfma_f32_16x16x32_bf16 v[8:11], v[136:139], v[212:215], v[8:11]
	v_mfma_f32_16x16x32_bf16 v[60:63], v[132:135], v[180:183], v[60:63]
	v_mfma_f32_16x16x32_bf16 v[56:59], v[140:143], v[180:183], v[56:59]
	v_mfma_f32_16x16x32_bf16 v[44:47], v[132:135], v[198:201], v[44:47]
	v_mfma_f32_16x16x32_bf16 v[40:43], v[140:143], v[198:201], v[40:43]
	v_mfma_f32_16x16x32_bf16 v[28:31], v[132:135], v[208:211], v[28:31]
	v_mfma_f32_16x16x32_bf16 v[24:27], v[140:143], v[208:211], v[24:27]
	v_mfma_f32_16x16x32_bf16 v[12:15], v[132:135], v[216:219], v[12:15]
	v_mfma_f32_16x16x32_bf16 v[8:11], v[140:143], v[216:219], v[8:11]
	s_setprio 0
	s_setprio 1
	v_mfma_f32_16x16x32_bf16 v[52:55], v[144:147], v[176:179], v[52:55]
	v_mfma_f32_16x16x32_bf16 v[48:51], v[168:171], v[176:179], v[48:51]
	v_mfma_f32_16x16x32_bf16 v[36:39], v[144:147], v[192:195], v[36:39]
	v_mfma_f32_16x16x32_bf16 v[32:35], v[168:171], v[192:195], v[32:35]
	v_mfma_f32_16x16x32_bf16 v[20:23], v[144:147], v[204:207], v[20:23]
	v_mfma_f32_16x16x32_bf16 v[16:19], v[168:171], v[204:207], v[16:19]
	v_mfma_f32_16x16x32_bf16 v[4:7], v[144:147], v[212:215], v[4:7]
	v_mfma_f32_16x16x32_bf16 v[0:3], v[168:171], v[212:215], v[0:3]
	v_mfma_f32_16x16x32_bf16 v[52:55], v[148:151], v[180:183], v[52:55]
	v_mfma_f32_16x16x32_bf16 v[48:51], v[172:175], v[180:183], v[48:51]
	v_mfma_f32_16x16x32_bf16 v[36:39], v[148:151], v[198:201], v[36:39]
	v_mfma_f32_16x16x32_bf16 v[32:35], v[172:175], v[198:201], v[32:35]
	v_mfma_f32_16x16x32_bf16 v[20:23], v[148:151], v[208:211], v[20:23]
	v_mfma_f32_16x16x32_bf16 v[16:19], v[172:175], v[208:211], v[16:19]
	v_mfma_f32_16x16x32_bf16 v[4:7], v[148:151], v[216:219], v[4:7]
	v_mfma_f32_16x16x32_bf16 v[0:3], v[172:175], v[216:219], v[0:3]
	s_setprio 0
	s_add_i32 s56, s56, 2
	s_add_u32 s54, s54, 0x100
	s_addc_u32 s55, s55, 0
	s_cmp_gt_u32 s56, 41
	s_mov_b64 s[30:31], s[34:35]
	s_barrier
	s_cbranch_scc0 .LBB0_1124
	s_and_b64 vcc, exec, s[26:27]
	s_cbranch_vccz .LBB0_1127
	s_barrier
